# v13: sc1 scope on the attention loop K/V LDS-DMA loads (tiles are read once per CU: no vector-L1 allocation)
# baseline (speedup 1.0000x reference)
; #define SBAR() __builtin_amdgcn_sched_barrier(0)
; #define PVR(S, DA, DB, vbase) do { S[0] = tr_read<v_rd_off(DA, 0, 0)>(vbase); S[1] = tr_read<v_rd_off(DA, 0, 1)>(vbase); S[2] = tr_read<v_rd_off(DB, 0, 0)>(vbase); S[3] = tr_read<v_rd_off(DB, 0, 1)>(vbase); \
;     S[4] = tr_read<v_rd_off(DA, 1, 0)>(vbase); S[5] = tr_read<v_rd_off(DA, 1, 1)>(vbase); S[6] = tr_read<v_rd_off(DB, 1, 0)>(vbase); S[7] = tr_read<v_rd_off(DB, 1, 1)>(vbase); } while (0)
; #define RAWBAR() do { asm volatile("s_waitcnt lgkmcnt(0)" ::: "memory"); __builtin_amdgcn_s_barrier(); asm volatile("" ::: "memory"); } while (0)
; #define RAWBAR() do { asm volatile("s_waitcnt lgkmcnt(0)" ::: "memory"); __builtin_amdgcn_s_barrier(); asm volatile("" ::: "memory"); } while (0)
; #define RAWBAR() do { asm volatile("s_waitcnt lgkmcnt(0)" ::: "memory"); __builtin_amdgcn_s_barrier(); asm volatile("" ::: "memory"); } while (0)
; #define RAWBAR() do { asm volatile("s_waitcnt lgkmcnt(0)" ::: "memory"); __builtin_amdgcn_s_barrier(); asm volatile("" ::: "memory"); } while (0)
; #define RAWBAR() do { asm volatile("s_waitcnt lgkmcnt(0)" ::: "memory"); __builtin_amdgcn_s_barrier(); asm volatile("" ::: "memory"); } while (0)
; template <int MODE> ...
;     ...
;   for (int j = 0; j < NT; ++j) {
;     const int buf = j & 1;
;     if (j + 1 < NT) { STAGE((j + 1) * KVBLK, buf ^ 1); }
;     const char* Kb = K_lds + buf * 16384;
;     f32x16 pe = {}, po = {};
; #pragma unroll
;     for (int d0 = 0; d0 < 8; d0 += 2) {
;       const bf16x8 k0 = *reinterpret_cast<const bf16x8*>(Kb + KSWZ(krow, (d0 * 16 + hi * 8) * 2));
;       const bf16x8 k1 = *reinterpret_cast<const bf16x8*>(Kb + KSWZ(krow, ((d0 + 1) * 16 + hi * 8) * 2));
;       pe = __builtin_amdgcn_mfma_f32_32x32x16_bf16(k0, qr[d0], pe, 0, 0, 0);
;       po = __builtin_amdgcn_mfma_f32_32x32x16_bf16(k1, qr[d0 + 1], po, 0, 0, 0); }
;     const int vo = vb0 + buf * 32768;
;     s16x4 R0_[8], R1_[8];
;     PVR(R0_, 0, 1, vo);
;     f32x16 p;
; #pragma unroll
;     for (int r = 0; r < 16; ++r) p[r] = __builtin_amdgcn_exp2f(fmaf(pe[r] + po[r], C, negMc));
;     float ps = 0.f;
; #pragma unroll
;     for (int r = 0; r < 16; ++r) ps += p[r];
;     lsum += ps;
;     const bf16x8 own0 = pk8(p, 0), own1 = pk8(p, 8);
;     SBAR();
;     PV_TAIL4(o, vo, vo + 16384, own0, own1);
;     asm volatile("s_waitcnt vmcnt(0)" ::: "memory");
;     RAWBAR();
;   }
.LBB0_1019:
	ds_read_b128 v[226:229], v225 offset:16384
	ds_read_b128 v[230:233], v223 offset:16384
	ds_read_b128 v[234:237], v222 offset:16384
	ds_read_b128 v[238:241], v221 offset:16384
	s_mov_b32 m0, s24
	s_nop 0
	global_load_lds_dwordx4 v220, s[86:87] sc1
	s_add_i32 m0, s24, 0x2000
	s_nop 0
	global_load_lds_dwordx4 v219, s[86:87] sc1
	v_exp_f32_e32 v144, v144
	v_exp_f32_e32 v145, v145
	v_exp_f32_e32 v146, v146
	v_exp_f32_e32 v147, v147
	s_waitcnt lgkmcnt(2)
	v_mfma_f32_32x32x16_bf16 v[128:143], v[226:229], v[188:191], 0
	v_mfma_f32_32x32x16_bf16 v[128:143], v[230:233], v[184:187], v[128:143]
	ds_read_b128 v[226:229], v225 offset:16512
	ds_read_b128 v[230:233], v223 offset:16512
	v_exp_f32_e32 v148, v148
	v_exp_f32_e32 v149, v149
	v_exp_f32_e32 v150, v150
	v_exp_f32_e32 v151, v151
	v_add_f32_e32 v246, v144, v145
	v_add_f32_e32 v246, v146, v246
	v_add_f32_e32 v246, v147, v246
	s_waitcnt lgkmcnt(2)
	v_mfma_f32_32x32x16_bf16 v[128:143], v[234:237], v[180:183], v[128:143]
	v_mfma_f32_32x32x16_bf16 v[128:143], v[238:241], v[176:179], v[128:143]
	ds_read_b128 v[234:237], v222 offset:16512
	ds_read_b128 v[238:241], v221 offset:16512
	v_exp_f32_e32 v152, v152
	v_exp_f32_e32 v153, v153
	v_exp_f32_e32 v154, v154
	v_exp_f32_e32 v155, v155
	v_add_f32_e32 v246, v148, v246
	v_add_f32_e32 v246, v149, v246
	v_add_f32_e32 v246, v150, v246
	v_add_f32_e32 v246, v151, v246
	s_waitcnt lgkmcnt(2)
	v_mfma_f32_32x32x16_bf16 v[128:143], v[226:229], v[172:175], v[128:143]
	v_mfma_f32_32x32x16_bf16 v[128:143], v[230:233], v[168:171], v[128:143]
	v_exp_f32_e32 v156, v156
	v_exp_f32_e32 v157, v157
	v_exp_f32_e32 v158, v158
	v_exp_f32_e32 v159, v159
	v_add_f32_e32 v246, v152, v246
	v_add_f32_e32 v246, v153, v246
	v_add_f32_e32 v246, v154, v246
	v_add_f32_e32 v246, v155, v246
	v_cvt_pk_bf16_f32 v226, v144, v145
	v_cvt_pk_bf16_f32 v227, v146, v147
	v_cvt_pk_bf16_f32 v228, v148, v149
	v_cvt_pk_bf16_f32 v229, v150, v151
	s_waitcnt lgkmcnt(0)
	v_mfma_f32_32x32x16_bf16 v[128:143], v[234:237], v[164:167], v[128:143]
	v_mfma_f32_32x32x16_bf16 v[128:143], v[238:241], v[160:163], v[128:143]
	v_add_u32_e32 v245, s84, v214
	s_add_i32 s85, s84, 0x8000
	s_cmp_eq_u32 s85, 0x18000
	s_cselect_b32 s85, 0, s85
	ds_read_b64_tr_b16 v[234:235], v245 offset:0
	ds_read_b64_tr_b16 v[236:237], v245 offset:2048
	ds_read_b64_tr_b16 v[238:239], v245 offset:512
	ds_read_b64_tr_b16 v[240:241], v245 offset:2560
	ds_read_b64_tr_b16 v[144:145], v245 offset:4096
	ds_read_b64_tr_b16 v[146:147], v245 offset:6144
	ds_read_b64_tr_b16 v[148:149], v245 offset:4608
	ds_read_b64_tr_b16 v[150:151], v245 offset:6656
	v_add_f32_e32 v246, v156, v246
	v_add_f32_e32 v246, v157, v246
	v_add_f32_e32 v246, v158, v246
	v_add_f32_e32 v246, v159, v246
	v_cvt_pk_bf16_f32 v230, v152, v153
	v_cvt_pk_bf16_f32 v231, v154, v155
	v_cvt_pk_bf16_f32 v232, v156, v157
	v_cvt_pk_bf16_f32 v233, v158, v159
	v_add_f32_e32 v215, v215, v246
	ds_read_b64_tr_b16 v[152:153], v245 offset:1024
	ds_read_b64_tr_b16 v[154:155], v245 offset:3072
	ds_read_b64_tr_b16 v[156:157], v245 offset:1536
	ds_read_b64_tr_b16 v[158:159], v245 offset:3584
	s_waitcnt lgkmcnt(8)
	v_mfma_f32_32x32x16_bf16 v[112:127], v[226:229], v[234:237], v[112:127]
	v_mfma_f32_32x32x16_bf16 v[96:111], v[226:229], v[238:241], v[96:111]
	ds_read_b64_tr_b16 v[234:235], v245 offset:5120
	ds_read_b64_tr_b16 v[236:237], v245 offset:7168
	ds_read_b64_tr_b16 v[238:239], v245 offset:5632
	ds_read_b64_tr_b16 v[240:241], v245 offset:7680
	s_add_i32 s41, s85, s24
	s_add_i32 m0, s41, 0x8000
	s_nop 0
	global_load_lds_dwordx4 v218, s[2:3] sc1
	s_waitcnt lgkmcnt(8)
	v_mfma_f32_32x32x16_bf16 v[112:127], v[230:233], v[144:147], v[112:127]
	v_mfma_f32_32x32x16_bf16 v[96:111], v[230:233], v[148:151], v[96:111]
	ds_read_b64_tr_b16 v[144:145], v245 offset:16384
	ds_read_b64_tr_b16 v[146:147], v245 offset:18432
	ds_read_b64_tr_b16 v[148:149], v245 offset:16896
	ds_read_b64_tr_b16 v[150:151], v245 offset:18944
	s_add_i32 s41, s85, s24
	s_add_i32 m0, s41, 0xa000
	s_nop 0
	global_load_lds_dwordx4 v217, s[2:3] sc1
	s_waitcnt lgkmcnt(8)
	v_mfma_f32_32x32x16_bf16 v[80:95], v[226:229], v[152:155], v[80:95]
	v_mfma_f32_32x32x16_bf16 v[64:79], v[226:229], v[156:159], v[64:79]
	ds_read_b64_tr_b16 v[152:153], v245 offset:20480
	ds_read_b64_tr_b16 v[154:155], v245 offset:22528
	ds_read_b64_tr_b16 v[156:157], v245 offset:20992
	ds_read_b64_tr_b16 v[158:159], v245 offset:23040
	s_add_i32 s41, s85, s24
	s_add_i32 m0, s41, 0xc000
	s_nop 0
	global_load_lds_dwordx4 v242, s[2:3] sc1
	s_waitcnt lgkmcnt(8)
	v_mfma_f32_32x32x16_bf16 v[80:95], v[230:233], v[234:237], v[80:95]
	v_mfma_f32_32x32x16_bf16 v[64:79], v[230:233], v[238:241], v[64:79]
	ds_read_b64_tr_b16 v[234:235], v245 offset:17408
	ds_read_b64_tr_b16 v[236:237], v245 offset:19456
	ds_read_b64_tr_b16 v[238:239], v245 offset:17920
	ds_read_b64_tr_b16 v[240:241], v245 offset:19968
	s_add_i32 s41, s85, s24
	s_add_i32 m0, s41, 0xe000
	s_nop 0
	global_load_lds_dwordx4 v243, s[2:3] sc1
	s_waitcnt lgkmcnt(8)
	v_mfma_f32_32x32x16_bf16 v[48:63], v[226:229], v[144:147], v[48:63]
	v_mfma_f32_32x32x16_bf16 v[32:47], v[226:229], v[148:151], v[32:47]
	ds_read_b64_tr_b16 v[144:145], v245 offset:21504
	ds_read_b64_tr_b16 v[146:147], v245 offset:23552
	ds_read_b64_tr_b16 v[148:149], v245 offset:22016
	ds_read_b64_tr_b16 v[150:151], v245 offset:24064
	s_waitcnt lgkmcnt(8)
	v_mfma_f32_32x32x16_bf16 v[48:63], v[230:233], v[152:155], v[48:63]
	v_mfma_f32_32x32x16_bf16 v[32:47], v[230:233], v[156:159], v[32:47]
	s_waitcnt lgkmcnt(0)
	v_mfma_f32_32x32x16_bf16 v[16:31], v[226:229], v[234:237], v[16:31]
	s_waitcnt vmcnt(0)
	s_barrier
; #define SBAR() __builtin_amdgcn_sched_barrier(0)
; #define PVR(S, DA, DB, vbase) do { S[0] = tr_read<v_rd_off(DA, 0, 0)>(vbase); S[1] = tr_read<v_rd_off(DA, 0, 1)>(vbase); S[2] = tr_read<v_rd_off(DB, 0, 0)>(vbase); S[3] = tr_read<v_rd_off(DB, 0, 1)>(vbase); \
;     S[4] = tr_read<v_rd_off(DA, 1, 0)>(vbase); S[5] = tr_read<v_rd_off(DA, 1, 1)>(vbase); S[6] = tr_read<v_rd_off(DB, 1, 0)>(vbase); S[7] = tr_read<v_rd_off(DB, 1, 1)>(vbase); } while (0)
; #define RAWBAR() do { asm volatile("s_waitcnt lgkmcnt(0)" ::: "memory"); __builtin_amdgcn_s_barrier(); asm volatile("" ::: "memory"); } while (0)
; #define RAWBAR() do { asm volatile("s_waitcnt lgkmcnt(0)" ::: "memory"); __builtin_amdgcn_s_barrier(); asm volatile("" ::: "memory"); } while (0)
; #define RAWBAR() do { asm volatile("s_waitcnt lgkmcnt(0)" ::: "memory"); __builtin_amdgcn_s_barrier(); asm volatile("" ::: "memory"); } while (0)
; #define RAWBAR() do { asm volatile("s_waitcnt lgkmcnt(0)" ::: "memory"); __builtin_amdgcn_s_barrier(); asm volatile("" ::: "memory"); } while (0)
; #define RAWBAR() do { asm volatile("s_waitcnt lgkmcnt(0)" ::: "memory"); __builtin_amdgcn_s_barrier(); asm volatile("" ::: "memory"); } while (0)
; template <int MODE> ...
;     ...
;   for (int j = 0; j < NT; ++j) {
;     const int buf = j & 1;
;     if (j + 1 < NT) { STAGE((j + 1) * KVBLK, buf ^ 1); }
;     const char* Kb = K_lds + buf * 16384;
;     f32x16 pe = {}, po = {};
; #pragma unroll
;     for (int d0 = 0; d0 < 8; d0 += 2) {
;       const bf16x8 k0 = *reinterpret_cast<const bf16x8*>(Kb + KSWZ(krow, (d0 * 16 + hi * 8) * 2));
;       const bf16x8 k1 = *reinterpret_cast<const bf16x8*>(Kb + KSWZ(krow, ((d0 + 1) * 16 + hi * 8) * 2));
;       pe = __builtin_amdgcn_mfma_f32_32x32x16_bf16(k0, qr[d0], pe, 0, 0, 0);
;       po = __builtin_amdgcn_mfma_f32_32x32x16_bf16(k1, qr[d0 + 1], po, 0, 0, 0); }
;     const int vo = vb0 + buf * 32768;
;     s16x4 R0_[8], R1_[8];
;     PVR(R0_, 0, 1, vo);
;     f32x16 p;
; #pragma unroll
;     for (int r = 0; r < 16; ++r) p[r] = __builtin_amdgcn_exp2f(fmaf(pe[r] + po[r], C, negMc));
;     float ps = 0.f;
; #pragma unroll
;     for (int r = 0; r < 16; ++r) ps += p[r];
;     lsum += ps;
;     const bf16x8 own0 = pk8(p, 0), own1 = pk8(p, 8);
;     SBAR();
;     PV_TAIL4(o, vo, vo + 16384, own0, own1);
;     asm volatile("s_waitcnt vmcnt(0)" ::: "memory");
;     RAWBAR();
;   }
	s_add_u32 s86, s86, 0x4000
	s_addc_u32 s87, s87, 0
	s_add_u32 s2, s2, 0x8000
	s_addc_u32 s3, s3, 0
	v_mfma_f32_32x32x16_bf16 v[0:15], v[226:229], v[238:241], v[0:15]
	v_mfma_f32_32x32x16_bf16 v[16:31], v[230:233], v[144:147], v[16:31]
	v_mfma_f32_32x32x16_bf16 v[0:15], v[230:233], v[148:151], v[0:15]
	s_add_i32 s84, s84, 0x8000
	s_cmp_eq_u32 s84, 0x18000
	s_cselect_b32 s84, 0, s84
	ds_read_b128 v[226:229], v225 offset:0
	ds_read_b128 v[230:233], v223 offset:0
	ds_read_b128 v[234:237], v222 offset:0
	ds_read_b128 v[238:241], v221 offset:0
	s_add_i32 m0, s24, 0x4000
	s_nop 0
	global_load_lds_dwordx4 v220, s[86:87] sc1
	s_add_i32 m0, s24, 0x6000
	s_nop 0
	global_load_lds_dwordx4 v219, s[86:87] sc1
	v_exp_f32_e32 v128, v128
	v_exp_f32_e32 v129, v129
	v_exp_f32_e32 v130, v130
	v_exp_f32_e32 v131, v131
	s_waitcnt lgkmcnt(2)
	v_mfma_f32_32x32x16_bf16 v[144:159], v[226:229], v[188:191], 0
	v_mfma_f32_32x32x16_bf16 v[144:159], v[230:233], v[184:187], v[144:159]
	ds_read_b128 v[226:229], v225 offset:128
	ds_read_b128 v[230:233], v223 offset:128
	v_exp_f32_e32 v132, v132
	v_exp_f32_e32 v133, v133
	v_exp_f32_e32 v134, v134
	v_exp_f32_e32 v135, v135
	v_add_f32_e32 v246, v128, v129
	v_add_f32_e32 v246, v130, v246
	v_add_f32_e32 v246, v131, v246
	s_waitcnt lgkmcnt(2)
	v_mfma_f32_32x32x16_bf16 v[144:159], v[234:237], v[180:183], v[144:159]
	v_mfma_f32_32x32x16_bf16 v[144:159], v[238:241], v[176:179], v[144:159]
	ds_read_b128 v[234:237], v222 offset:128
	ds_read_b128 v[238:241], v221 offset:128
	v_exp_f32_e32 v136, v136
	v_exp_f32_e32 v137, v137
	v_exp_f32_e32 v138, v138
	v_exp_f32_e32 v139, v139
	v_add_f32_e32 v246, v132, v246
	v_add_f32_e32 v246, v133, v246
	v_add_f32_e32 v246, v134, v246
	v_add_f32_e32 v246, v135, v246
	s_waitcnt lgkmcnt(2)
	v_mfma_f32_32x32x16_bf16 v[144:159], v[226:229], v[172:175], v[144:159]
	v_mfma_f32_32x32x16_bf16 v[144:159], v[230:233], v[168:171], v[144:159]
	v_exp_f32_e32 v140, v140
	v_exp_f32_e32 v141, v141
	v_exp_f32_e32 v142, v142
	v_exp_f32_e32 v143, v143
	v_add_f32_e32 v246, v136, v246
	v_add_f32_e32 v246, v137, v246
	v_add_f32_e32 v246, v138, v246
	v_add_f32_e32 v246, v139, v246
	v_cvt_pk_bf16_f32 v226, v128, v129
	v_cvt_pk_bf16_f32 v227, v130, v131
	v_cvt_pk_bf16_f32 v228, v132, v133
	v_cvt_pk_bf16_f32 v229, v134, v135
	s_waitcnt lgkmcnt(0)
	v_mfma_f32_32x32x16_bf16 v[144:159], v[234:237], v[164:167], v[144:159]
	v_mfma_f32_32x32x16_bf16 v[144:159], v[238:241], v[160:163], v[144:159]
	v_add_u32_e32 v245, s84, v214
	s_add_i32 s85, s84, 0x8000
	s_cmp_eq_u32 s85, 0x18000
	s_cselect_b32 s85, 0, s85
	ds_read_b64_tr_b16 v[234:235], v245 offset:0
	ds_read_b64_tr_b16 v[236:237], v245 offset:2048
	ds_read_b64_tr_b16 v[238:239], v245 offset:512
	ds_read_b64_tr_b16 v[240:241], v245 offset:2560
	ds_read_b64_tr_b16 v[128:129], v245 offset:4096
	ds_read_b64_tr_b16 v[130:131], v245 offset:6144
	ds_read_b64_tr_b16 v[132:133], v245 offset:4608
	ds_read_b64_tr_b16 v[134:135], v245 offset:6656
	v_add_f32_e32 v246, v140, v246
	v_add_f32_e32 v246, v141, v246
	v_add_f32_e32 v246, v142, v246
	v_add_f32_e32 v246, v143, v246
	v_cvt_pk_bf16_f32 v230, v136, v137
	v_cvt_pk_bf16_f32 v231, v138, v139
	v_cvt_pk_bf16_f32 v232, v140, v141
	v_cvt_pk_bf16_f32 v233, v142, v143
	v_add_f32_e32 v215, v215, v246
	ds_read_b64_tr_b16 v[136:137], v245 offset:1024
	ds_read_b64_tr_b16 v[138:139], v245 offset:3072
	ds_read_b64_tr_b16 v[140:141], v245 offset:1536
	ds_read_b64_tr_b16 v[142:143], v245 offset:3584
	s_waitcnt lgkmcnt(8)
	v_mfma_f32_32x32x16_bf16 v[112:127], v[226:229], v[234:237], v[112:127]
	v_mfma_f32_32x32x16_bf16 v[96:111], v[226:229], v[238:241], v[96:111]
	ds_read_b64_tr_b16 v[234:235], v245 offset:5120
	ds_read_b64_tr_b16 v[236:237], v245 offset:7168
	ds_read_b64_tr_b16 v[238:239], v245 offset:5632
	ds_read_b64_tr_b16 v[240:241], v245 offset:7680
	s_add_i32 s41, s85, s24
	s_add_i32 m0, s41, 0x8000
	s_nop 0
	global_load_lds_dwordx4 v218, s[2:3] sc1
	s_waitcnt lgkmcnt(8)
	v_mfma_f32_32x32x16_bf16 v[112:127], v[230:233], v[128:131], v[112:127]
	v_mfma_f32_32x32x16_bf16 v[96:111], v[230:233], v[132:135], v[96:111]
	ds_read_b64_tr_b16 v[128:129], v245 offset:16384
	ds_read_b64_tr_b16 v[130:131], v245 offset:18432
	ds_read_b64_tr_b16 v[132:133], v245 offset:16896
	ds_read_b64_tr_b16 v[134:135], v245 offset:18944
	s_add_i32 s41, s85, s24
	s_add_i32 m0, s41, 0xa000
	s_nop 0
	global_load_lds_dwordx4 v217, s[2:3] sc1
	s_waitcnt lgkmcnt(8)
	v_mfma_f32_32x32x16_bf16 v[80:95], v[226:229], v[136:139], v[80:95]
	v_mfma_f32_32x32x16_bf16 v[64:79], v[226:229], v[140:143], v[64:79]
	ds_read_b64_tr_b16 v[136:137], v245 offset:20480
	ds_read_b64_tr_b16 v[138:139], v245 offset:22528
	ds_read_b64_tr_b16 v[140:141], v245 offset:20992
	ds_read_b64_tr_b16 v[142:143], v245 offset:23040
	s_add_i32 s41, s85, s24
	s_add_i32 m0, s41, 0xc000
	s_nop 0
	global_load_lds_dwordx4 v242, s[2:3] sc1
	s_waitcnt lgkmcnt(8)
	v_mfma_f32_32x32x16_bf16 v[80:95], v[230:233], v[234:237], v[80:95]
	v_mfma_f32_32x32x16_bf16 v[64:79], v[230:233], v[238:241], v[64:79]
	ds_read_b64_tr_b16 v[234:235], v245 offset:17408
	ds_read_b64_tr_b16 v[236:237], v245 offset:19456
	ds_read_b64_tr_b16 v[238:239], v245 offset:17920
	ds_read_b64_tr_b16 v[240:241], v245 offset:19968
	s_add_i32 s41, s85, s24
	s_add_i32 m0, s41, 0xe000
	s_nop 0
	global_load_lds_dwordx4 v243, s[2:3] sc1
	s_waitcnt lgkmcnt(8)
	v_mfma_f32_32x32x16_bf16 v[48:63], v[226:229], v[128:131], v[48:63]
	v_mfma_f32_32x32x16_bf16 v[32:47], v[226:229], v[132:135], v[32:47]
	ds_read_b64_tr_b16 v[128:129], v245 offset:21504
	ds_read_b64_tr_b16 v[130:131], v245 offset:23552
	ds_read_b64_tr_b16 v[132:133], v245 offset:22016
	ds_read_b64_tr_b16 v[134:135], v245 offset:24064
	s_waitcnt lgkmcnt(8)
	v_mfma_f32_32x32x16_bf16 v[48:63], v[230:233], v[136:139], v[48:63]
	v_mfma_f32_32x32x16_bf16 v[32:47], v[230:233], v[140:143], v[32:47]
	s_waitcnt lgkmcnt(0)
	v_mfma_f32_32x32x16_bf16 v[16:31], v[226:229], v[234:237], v[16:31]
	s_waitcnt vmcnt(0)
	s_barrier
	s_add_u32 s86, s86, 0x4000
	s_addc_u32 s87, s87, 0
	s_add_u32 s2, s2, 0x8000
	s_addc_u32 s3, s3, 0
	v_mfma_f32_32x32x16_bf16 v[0:15], v[226:229], v[238:241], v[0:15]
	v_mfma_f32_32x32x16_bf16 v[16:31], v[230:233], v[128:131], v[16:31]
	v_mfma_f32_32x32x16_bf16 v[0:15], v[230:233], v[132:135], v[0:15]
	s_add_i32 s84, s84, 0x8000
	s_cmp_eq_u32 s84, 0x18000
	s_cselect_b32 s84, 0, s84
	s_add_i32 s25, s25, 1
	s_cmpk_eq_i32 s25, 0x82
	s_cbranch_scc0 .LBB0_1019
	s_barrier
	s_branch .Lattn_join_m0
; #define SBAR() __builtin_amdgcn_sched_barrier(0)
; #define PVR(S, DA, DB, vbase) do { S[0] = tr_read<v_rd_off(DA, 0, 0)>(vbase); S[1] = tr_read<v_rd_off(DA, 0, 1)>(vbase); S[2] = tr_read<v_rd_off(DB, 0, 0)>(vbase); S[3] = tr_read<v_rd_off(DB, 0, 1)>(vbase); \
;     S[4] = tr_read<v_rd_off(DA, 1, 0)>(vbase); S[5] = tr_read<v_rd_off(DA, 1, 1)>(vbase); S[6] = tr_read<v_rd_off(DB, 1, 0)>(vbase); S[7] = tr_read<v_rd_off(DB, 1, 1)>(vbase); } while (0)
; #define RAWBAR() do { asm volatile("s_waitcnt lgkmcnt(0)" ::: "memory"); __builtin_amdgcn_s_barrier(); asm volatile("" ::: "memory"); } while (0)
; #define RAWBAR() do { asm volatile("s_waitcnt lgkmcnt(0)" ::: "memory"); __builtin_amdgcn_s_barrier(); asm volatile("" ::: "memory"); } while (0)
; #define RAWBAR() do { asm volatile("s_waitcnt lgkmcnt(0)" ::: "memory"); __builtin_amdgcn_s_barrier(); asm volatile("" ::: "memory"); } while (0)
; #define RAWBAR() do { asm volatile("s_waitcnt lgkmcnt(0)" ::: "memory"); __builtin_amdgcn_s_barrier(); asm volatile("" ::: "memory"); } while (0)
; #define RAWBAR() do { asm volatile("s_waitcnt lgkmcnt(0)" ::: "memory"); __builtin_amdgcn_s_barrier(); asm volatile("" ::: "memory"); } while (0)
; template <int MODE> ...
;     ...
;   for (int j = 0; j < NT; ++j) {
;     const int buf = j & 1;
;     if (j + 1 < NT) { STAGE((j + 1) * KVBLK, buf ^ 1); }
;     const char* Kb = K_lds + buf * 16384;
;     f32x16 pe = {}, po = {};
; #pragma unroll
;     for (int d0 = 0; d0 < 8; d0 += 2) {
;       const bf16x8 k0 = *reinterpret_cast<const bf16x8*>(Kb + KSWZ(krow, (d0 * 16 + hi * 8) * 2));
;       const bf16x8 k1 = *reinterpret_cast<const bf16x8*>(Kb + KSWZ(krow, ((d0 + 1) * 16 + hi * 8) * 2));
;       pe = __builtin_amdgcn_mfma_f32_32x32x16_bf16(k0, qr[d0], pe, 0, 0, 0);
;       po = __builtin_amdgcn_mfma_f32_32x32x16_bf16(k1, qr[d0 + 1], po, 0, 0, 0); }
;     const int vo = vb0 + buf * 32768;
;     s16x4 R0_[8], R1_[8];
;     PVR(R0_, 0, 1, vo);
;     f32x16 p;
; #pragma unroll
;     for (int r = 0; r < 16; ++r) p[r] = __builtin_amdgcn_exp2f(fmaf(pe[r] + po[r], C, negMc));
;     float ps = 0.f;
; #pragma unroll
;     for (int r = 0; r < 16; ++r) ps += p[r];
;     lsum += ps;
;     const bf16x8 own0 = pk8(p, 0), own1 = pk8(p, 8);
;     SBAR();
;     PV_TAIL4(o, vo, vo + 16384, own0, own1);
;     asm volatile("s_waitcnt vmcnt(0)" ::: "memory");
;     RAWBAR();
;   }
.LattnBpre_m0:
	s_mov_b32 m0, s24
	s_nop 0
	global_load_lds_dwordx4 v220, s[86:87] sc1
	s_add_i32 m0, s24, 0x2000
	s_nop 0
	global_load_lds_dwordx4 v219, s[86:87] sc1
	s_add_i32 s85, s84, 0x8000
	s_cmp_eq_u32 s85, 0x18000
	s_cselect_b32 s85, 0, s85
	s_add_i32 s41, s85, s24
	s_add_i32 m0, s41, 0x8000
	s_nop 0
	global_load_lds_dwordx4 v218, s[2:3] sc1
	s_add_i32 s41, s85, s24
	s_add_i32 m0, s41, 0xa000
	s_nop 0
	global_load_lds_dwordx4 v217, s[2:3] sc1
	s_add_i32 s41, s85, s24
	s_add_i32 m0, s41, 0xc000
	s_nop 0
	global_load_lds_dwordx4 v242, s[2:3] sc1
	s_add_i32 s41, s85, s24
	s_add_i32 m0, s41, 0xe000
	s_nop 0
	global_load_lds_dwordx4 v243, s[2:3] sc1
.LattnB_m0:
	ds_read_b128 v[226:229], v225 offset:16384
	ds_read_b128 v[230:233], v223 offset:16384
	ds_read_b128 v[234:237], v222 offset:16384
	ds_read_b128 v[238:241], v221 offset:16384
	v_exp_f32_e32 v144, v144
	v_exp_f32_e32 v145, v145
	v_exp_f32_e32 v146, v146
	v_exp_f32_e32 v147, v147
	s_waitcnt lgkmcnt(2)
	v_mfma_f32_32x32x16_bf16 v[128:143], v[226:229], v[188:191], 0
	v_mfma_f32_32x32x16_bf16 v[128:143], v[230:233], v[184:187], v[128:143]
	ds_read_b128 v[226:229], v225 offset:16512
	ds_read_b128 v[230:233], v223 offset:16512
	v_exp_f32_e32 v148, v148
	v_exp_f32_e32 v149, v149
	v_exp_f32_e32 v150, v150
	v_exp_f32_e32 v151, v151
	v_add_f32_e32 v246, v144, v145
	v_add_f32_e32 v246, v146, v246
	v_add_f32_e32 v246, v147, v246
	s_waitcnt lgkmcnt(2)
	v_mfma_f32_32x32x16_bf16 v[128:143], v[234:237], v[180:183], v[128:143]
	v_mfma_f32_32x32x16_bf16 v[128:143], v[238:241], v[176:179], v[128:143]
	ds_read_b128 v[234:237], v222 offset:16512
	ds_read_b128 v[238:241], v221 offset:16512
	v_exp_f32_e32 v152, v152
	v_exp_f32_e32 v153, v153
	v_exp_f32_e32 v154, v154
	v_exp_f32_e32 v155, v155
	v_add_f32_e32 v246, v148, v246
	v_add_f32_e32 v246, v149, v246
	v_add_f32_e32 v246, v150, v246
	v_add_f32_e32 v246, v151, v246
	s_waitcnt lgkmcnt(2)
	v_mfma_f32_32x32x16_bf16 v[128:143], v[226:229], v[172:175], v[128:143]
	v_mfma_f32_32x32x16_bf16 v[128:143], v[230:233], v[168:171], v[128:143]
	v_exp_f32_e32 v156, v156
	v_exp_f32_e32 v157, v157
	v_exp_f32_e32 v158, v158
	v_exp_f32_e32 v159, v159
	v_add_f32_e32 v246, v152, v246
	v_add_f32_e32 v246, v153, v246
	v_add_f32_e32 v246, v154, v246
	v_add_f32_e32 v246, v155, v246
	v_cvt_pk_bf16_f32 v226, v144, v145
	v_cvt_pk_bf16_f32 v227, v146, v147
	v_cvt_pk_bf16_f32 v228, v148, v149
	v_cvt_pk_bf16_f32 v229, v150, v151
	s_waitcnt lgkmcnt(0)
	v_mfma_f32_32x32x16_bf16 v[128:143], v[234:237], v[164:167], v[128:143]
	v_mfma_f32_32x32x16_bf16 v[128:143], v[238:241], v[160:163], v[128:143]
	s_waitcnt vmcnt(0)
	s_barrier
	s_add_u32 s86, s86, 0x4000
	s_addc_u32 s87, s87, 0
	s_add_u32 s2, s2, 0x8000
	s_addc_u32 s3, s3, 0
	s_add_i32 m0, s24, 0x4000
	s_nop 0
	global_load_lds_dwordx4 v220, s[86:87] sc1
	s_add_i32 m0, s24, 0x6000
	s_nop 0
	global_load_lds_dwordx4 v219, s[86:87] sc1
	v_add_u32_e32 v245, s84, v214
	s_sub_u32 s85, s84, 0x8000
	s_cmp_eq_u32 s84, 0
	s_cselect_b32 s85, 0x10000, s85
	ds_read_b64_tr_b16 v[234:235], v245 offset:0
	ds_read_b64_tr_b16 v[236:237], v245 offset:2048
	ds_read_b64_tr_b16 v[238:239], v245 offset:512
	ds_read_b64_tr_b16 v[240:241], v245 offset:2560
	ds_read_b64_tr_b16 v[144:145], v245 offset:4096
	ds_read_b64_tr_b16 v[146:147], v245 offset:6144
	ds_read_b64_tr_b16 v[148:149], v245 offset:4608
	ds_read_b64_tr_b16 v[150:151], v245 offset:6656
	v_add_f32_e32 v246, v156, v246
	v_add_f32_e32 v246, v157, v246
	v_add_f32_e32 v246, v158, v246
	v_add_f32_e32 v246, v159, v246
	v_cvt_pk_bf16_f32 v230, v152, v153
	v_cvt_pk_bf16_f32 v231, v154, v155
	v_cvt_pk_bf16_f32 v232, v156, v157
	v_cvt_pk_bf16_f32 v233, v158, v159
	v_add_f32_e32 v215, v215, v246
	ds_read_b64_tr_b16 v[152:153], v245 offset:1024
	ds_read_b64_tr_b16 v[154:155], v245 offset:3072
	ds_read_b64_tr_b16 v[156:157], v245 offset:1536
	ds_read_b64_tr_b16 v[158:159], v245 offset:3584
	s_waitcnt lgkmcnt(8)
	v_mfma_f32_32x32x16_bf16 v[112:127], v[226:229], v[234:237], v[112:127]
	v_mfma_f32_32x32x16_bf16 v[96:111], v[226:229], v[238:241], v[96:111]
	ds_read_b64_tr_b16 v[234:235], v245 offset:5120
	ds_read_b64_tr_b16 v[236:237], v245 offset:7168
	ds_read_b64_tr_b16 v[238:239], v245 offset:5632
	ds_read_b64_tr_b16 v[240:241], v245 offset:7680
	s_add_i32 s41, s85, s24
	s_add_i32 m0, s41, 0x8000
	s_nop 0
	global_load_lds_dwordx4 v218, s[2:3] sc1
	s_waitcnt lgkmcnt(8)
	v_mfma_f32_32x32x16_bf16 v[112:127], v[230:233], v[144:147], v[112:127]
	v_mfma_f32_32x32x16_bf16 v[96:111], v[230:233], v[148:151], v[96:111]
	ds_read_b64_tr_b16 v[144:145], v245 offset:16384
	ds_read_b64_tr_b16 v[146:147], v245 offset:18432
	ds_read_b64_tr_b16 v[148:149], v245 offset:16896
	ds_read_b64_tr_b16 v[150:151], v245 offset:18944
	s_add_i32 s41, s85, s24
	s_add_i32 m0, s41, 0xa000
	s_nop 0
	global_load_lds_dwordx4 v217, s[2:3] sc1
	s_waitcnt lgkmcnt(8)
	v_mfma_f32_32x32x16_bf16 v[80:95], v[226:229], v[152:155], v[80:95]
	v_mfma_f32_32x32x16_bf16 v[64:79], v[226:229], v[156:159], v[64:79]
	ds_read_b64_tr_b16 v[152:153], v245 offset:20480
	ds_read_b64_tr_b16 v[154:155], v245 offset:22528
	ds_read_b64_tr_b16 v[156:157], v245 offset:20992
	ds_read_b64_tr_b16 v[158:159], v245 offset:23040
	s_add_i32 s41, s85, s24
	s_add_i32 m0, s41, 0xc000
	s_nop 0
	global_load_lds_dwordx4 v242, s[2:3] sc1
	s_waitcnt lgkmcnt(8)
	v_mfma_f32_32x32x16_bf16 v[80:95], v[230:233], v[234:237], v[80:95]
	v_mfma_f32_32x32x16_bf16 v[64:79], v[230:233], v[238:241], v[64:79]
	ds_read_b64_tr_b16 v[234:235], v245 offset:17408
	ds_read_b64_tr_b16 v[236:237], v245 offset:19456
	ds_read_b64_tr_b16 v[238:239], v245 offset:17920
	ds_read_b64_tr_b16 v[240:241], v245 offset:19968
	s_add_i32 s41, s85, s24
	s_add_i32 m0, s41, 0xe000
	s_nop 0
	global_load_lds_dwordx4 v243, s[2:3] sc1
	s_waitcnt lgkmcnt(8)
; #define SBAR() __builtin_amdgcn_sched_barrier(0)
; #define PVR(S, DA, DB, vbase) do { S[0] = tr_read<v_rd_off(DA, 0, 0)>(vbase); S[1] = tr_read<v_rd_off(DA, 0, 1)>(vbase); S[2] = tr_read<v_rd_off(DB, 0, 0)>(vbase); S[3] = tr_read<v_rd_off(DB, 0, 1)>(vbase); \
;     S[4] = tr_read<v_rd_off(DA, 1, 0)>(vbase); S[5] = tr_read<v_rd_off(DA, 1, 1)>(vbase); S[6] = tr_read<v_rd_off(DB, 1, 0)>(vbase); S[7] = tr_read<v_rd_off(DB, 1, 1)>(vbase); } while (0)
; #define RAWBAR() do { asm volatile("s_waitcnt lgkmcnt(0)" ::: "memory"); __builtin_amdgcn_s_barrier(); asm volatile("" ::: "memory"); } while (0)
; #define RAWBAR() do { asm volatile("s_waitcnt lgkmcnt(0)" ::: "memory"); __builtin_amdgcn_s_barrier(); asm volatile("" ::: "memory"); } while (0)
; #define RAWBAR() do { asm volatile("s_waitcnt lgkmcnt(0)" ::: "memory"); __builtin_amdgcn_s_barrier(); asm volatile("" ::: "memory"); } while (0)
; #define RAWBAR() do { asm volatile("s_waitcnt lgkmcnt(0)" ::: "memory"); __builtin_amdgcn_s_barrier(); asm volatile("" ::: "memory"); } while (0)
; #define RAWBAR() do { asm volatile("s_waitcnt lgkmcnt(0)" ::: "memory"); __builtin_amdgcn_s_barrier(); asm volatile("" ::: "memory"); } while (0)
; template <int MODE> ...
;     ...
;   for (int j = 0; j < NT; ++j) {
;     const int buf = j & 1;
;     if (j + 1 < NT) { STAGE((j + 1) * KVBLK, buf ^ 1); }
;     const char* Kb = K_lds + buf * 16384;
;     f32x16 pe = {}, po = {};
; #pragma unroll
;     for (int d0 = 0; d0 < 8; d0 += 2) {
;       const bf16x8 k0 = *reinterpret_cast<const bf16x8*>(Kb + KSWZ(krow, (d0 * 16 + hi * 8) * 2));
;       const bf16x8 k1 = *reinterpret_cast<const bf16x8*>(Kb + KSWZ(krow, ((d0 + 1) * 16 + hi * 8) * 2));
;       pe = __builtin_amdgcn_mfma_f32_32x32x16_bf16(k0, qr[d0], pe, 0, 0, 0);
;       po = __builtin_amdgcn_mfma_f32_32x32x16_bf16(k1, qr[d0 + 1], po, 0, 0, 0); }
;     const int vo = vb0 + buf * 32768;
;     s16x4 R0_[8], R1_[8];
;     PVR(R0_, 0, 1, vo);
;     f32x16 p;
; #pragma unroll
;     for (int r = 0; r < 16; ++r) p[r] = __builtin_amdgcn_exp2f(fmaf(pe[r] + po[r], C, negMc));
;     float ps = 0.f;
; #pragma unroll
;     for (int r = 0; r < 16; ++r) ps += p[r];
;     lsum += ps;
;     const bf16x8 own0 = pk8(p, 0), own1 = pk8(p, 8);
;     SBAR();
;     PV_TAIL4(o, vo, vo + 16384, own0, own1);
;     asm volatile("s_waitcnt vmcnt(0)" ::: "memory");
;     RAWBAR();
;   }
	v_mfma_f32_32x32x16_bf16 v[48:63], v[226:229], v[144:147], v[48:63]
	v_mfma_f32_32x32x16_bf16 v[32:47], v[226:229], v[148:151], v[32:47]
	ds_read_b64_tr_b16 v[144:145], v245 offset:21504
	ds_read_b64_tr_b16 v[146:147], v245 offset:23552
	ds_read_b64_tr_b16 v[148:149], v245 offset:22016
	ds_read_b64_tr_b16 v[150:151], v245 offset:24064
	s_waitcnt lgkmcnt(8)
	v_mfma_f32_32x32x16_bf16 v[48:63], v[230:233], v[152:155], v[48:63]
	v_mfma_f32_32x32x16_bf16 v[32:47], v[230:233], v[156:159], v[32:47]
	s_waitcnt lgkmcnt(0)
	v_mfma_f32_32x32x16_bf16 v[16:31], v[226:229], v[234:237], v[16:31]
	v_mfma_f32_32x32x16_bf16 v[0:15], v[226:229], v[238:241], v[0:15]
	v_mfma_f32_32x32x16_bf16 v[16:31], v[230:233], v[144:147], v[16:31]
	v_mfma_f32_32x32x16_bf16 v[0:15], v[230:233], v[148:151], v[0:15]
	s_add_i32 s84, s84, 0x8000
	s_cmp_eq_u32 s84, 0x18000
	s_cselect_b32 s84, 0, s84
	ds_read_b128 v[226:229], v225 offset:0
	ds_read_b128 v[230:233], v223 offset:0
	ds_read_b128 v[234:237], v222 offset:0
	ds_read_b128 v[238:241], v221 offset:0
	v_exp_f32_e32 v128, v128
	v_exp_f32_e32 v129, v129
	v_exp_f32_e32 v130, v130
	v_exp_f32_e32 v131, v131
	s_waitcnt lgkmcnt(2)
	v_mfma_f32_32x32x16_bf16 v[144:159], v[226:229], v[188:191], 0
	v_mfma_f32_32x32x16_bf16 v[144:159], v[230:233], v[184:187], v[144:159]
	ds_read_b128 v[226:229], v225 offset:128
	ds_read_b128 v[230:233], v223 offset:128
	v_exp_f32_e32 v132, v132
	v_exp_f32_e32 v133, v133
	v_exp_f32_e32 v134, v134
	v_exp_f32_e32 v135, v135
	v_add_f32_e32 v246, v128, v129
	v_add_f32_e32 v246, v130, v246
	v_add_f32_e32 v246, v131, v246
	s_waitcnt lgkmcnt(2)
	v_mfma_f32_32x32x16_bf16 v[144:159], v[234:237], v[180:183], v[144:159]
	v_mfma_f32_32x32x16_bf16 v[144:159], v[238:241], v[176:179], v[144:159]
	ds_read_b128 v[234:237], v222 offset:128
	ds_read_b128 v[238:241], v221 offset:128
	v_exp_f32_e32 v136, v136
	v_exp_f32_e32 v137, v137
	v_exp_f32_e32 v138, v138
	v_exp_f32_e32 v139, v139
	v_add_f32_e32 v246, v132, v246
	v_add_f32_e32 v246, v133, v246
	v_add_f32_e32 v246, v134, v246
	v_add_f32_e32 v246, v135, v246
	s_waitcnt lgkmcnt(2)
	v_mfma_f32_32x32x16_bf16 v[144:159], v[226:229], v[172:175], v[144:159]
	v_mfma_f32_32x32x16_bf16 v[144:159], v[230:233], v[168:171], v[144:159]
	v_exp_f32_e32 v140, v140
	v_exp_f32_e32 v141, v141
	v_exp_f32_e32 v142, v142
	v_exp_f32_e32 v143, v143
	v_add_f32_e32 v246, v136, v246
	v_add_f32_e32 v246, v137, v246
	v_add_f32_e32 v246, v138, v246
	v_add_f32_e32 v246, v139, v246
	v_cvt_pk_bf16_f32 v226, v128, v129
	v_cvt_pk_bf16_f32 v227, v130, v131
	v_cvt_pk_bf16_f32 v228, v132, v133
	v_cvt_pk_bf16_f32 v229, v134, v135
	s_waitcnt lgkmcnt(0)
	v_mfma_f32_32x32x16_bf16 v[144:159], v[234:237], v[164:167], v[144:159]
	v_mfma_f32_32x32x16_bf16 v[144:159], v[238:241], v[160:163], v[144:159]
	s_waitcnt vmcnt(0)
	s_barrier
	s_add_u32 s86, s86, 0x4000
	s_addc_u32 s87, s87, 0
	s_add_u32 s2, s2, 0x8000
	s_addc_u32 s3, s3, 0
	s_mov_b32 m0, s24
	s_nop 0
	global_load_lds_dwordx4 v220, s[86:87] sc1
	s_add_i32 m0, s24, 0x2000
	s_nop 0
	global_load_lds_dwordx4 v219, s[86:87] sc1
	v_add_u32_e32 v245, s84, v214
	s_sub_u32 s85, s84, 0x8000
	s_cmp_eq_u32 s84, 0
	s_cselect_b32 s85, 0x10000, s85
	ds_read_b64_tr_b16 v[234:235], v245 offset:0
	ds_read_b64_tr_b16 v[236:237], v245 offset:2048
	ds_read_b64_tr_b16 v[238:239], v245 offset:512
	ds_read_b64_tr_b16 v[240:241], v245 offset:2560
	ds_read_b64_tr_b16 v[128:129], v245 offset:4096
	ds_read_b64_tr_b16 v[130:131], v245 offset:6144
	ds_read_b64_tr_b16 v[132:133], v245 offset:4608
	ds_read_b64_tr_b16 v[134:135], v245 offset:6656
	v_add_f32_e32 v246, v140, v246
	v_add_f32_e32 v246, v141, v246
	v_add_f32_e32 v246, v142, v246
	v_add_f32_e32 v246, v143, v246
	v_cvt_pk_bf16_f32 v230, v136, v137
	v_cvt_pk_bf16_f32 v231, v138, v139
	v_cvt_pk_bf16_f32 v232, v140, v141
	v_cvt_pk_bf16_f32 v233, v142, v143
	v_add_f32_e32 v215, v215, v246
	ds_read_b64_tr_b16 v[136:137], v245 offset:1024
	ds_read_b64_tr_b16 v[138:139], v245 offset:3072
	ds_read_b64_tr_b16 v[140:141], v245 offset:1536
	ds_read_b64_tr_b16 v[142:143], v245 offset:3584
	s_waitcnt lgkmcnt(8)
	v_mfma_f32_32x32x16_bf16 v[112:127], v[226:229], v[234:237], v[112:127]
	v_mfma_f32_32x32x16_bf16 v[96:111], v[226:229], v[238:241], v[96:111]
	ds_read_b64_tr_b16 v[234:235], v245 offset:5120
	ds_read_b64_tr_b16 v[236:237], v245 offset:7168
	ds_read_b64_tr_b16 v[238:239], v245 offset:5632
	ds_read_b64_tr_b16 v[240:241], v245 offset:7680
	s_add_i32 s41, s85, s24
	s_add_i32 m0, s41, 0x8000
	s_nop 0
	global_load_lds_dwordx4 v218, s[2:3] sc1
	s_waitcnt lgkmcnt(8)
	v_mfma_f32_32x32x16_bf16 v[112:127], v[230:233], v[128:131], v[112:127]
	v_mfma_f32_32x32x16_bf16 v[96:111], v[230:233], v[132:135], v[96:111]
	ds_read_b64_tr_b16 v[128:129], v245 offset:16384
	ds_read_b64_tr_b16 v[130:131], v245 offset:18432
	ds_read_b64_tr_b16 v[132:133], v245 offset:16896
	ds_read_b64_tr_b16 v[134:135], v245 offset:18944
	s_add_i32 s41, s85, s24
	s_add_i32 m0, s41, 0xa000
	s_nop 0
	global_load_lds_dwordx4 v217, s[2:3] sc1
	s_waitcnt lgkmcnt(8)
	v_mfma_f32_32x32x16_bf16 v[80:95], v[226:229], v[136:139], v[80:95]
	v_mfma_f32_32x32x16_bf16 v[64:79], v[226:229], v[140:143], v[64:79]
	ds_read_b64_tr_b16 v[136:137], v245 offset:20480
	ds_read_b64_tr_b16 v[138:139], v245 offset:22528
	ds_read_b64_tr_b16 v[140:141], v245 offset:20992
	ds_read_b64_tr_b16 v[142:143], v245 offset:23040
	s_add_i32 s41, s85, s24
	s_add_i32 m0, s41, 0xc000
	s_nop 0
	global_load_lds_dwordx4 v242, s[2:3] sc1
	s_waitcnt lgkmcnt(8)
	v_mfma_f32_32x32x16_bf16 v[80:95], v[230:233], v[234:237], v[80:95]
	v_mfma_f32_32x32x16_bf16 v[64:79], v[230:233], v[238:241], v[64:79]
	ds_read_b64_tr_b16 v[234:235], v245 offset:17408
	ds_read_b64_tr_b16 v[236:237], v245 offset:19456
	ds_read_b64_tr_b16 v[238:239], v245 offset:17920
	ds_read_b64_tr_b16 v[240:241], v245 offset:19968
	s_add_i32 s41, s85, s24
	s_add_i32 m0, s41, 0xe000
	s_nop 0
	global_load_lds_dwordx4 v243, s[2:3] sc1
	s_waitcnt lgkmcnt(8)
	v_mfma_f32_32x32x16_bf16 v[48:63], v[226:229], v[128:131], v[48:63]
	v_mfma_f32_32x32x16_bf16 v[32:47], v[226:229], v[132:135], v[32:47]
	ds_read_b64_tr_b16 v[128:129], v245 offset:21504
	ds_read_b64_tr_b16 v[130:131], v245 offset:23552
	ds_read_b64_tr_b16 v[132:133], v245 offset:22016
	ds_read_b64_tr_b16 v[134:135], v245 offset:24064
	s_waitcnt lgkmcnt(8)
	v_mfma_f32_32x32x16_bf16 v[48:63], v[230:233], v[136:139], v[48:63]
	v_mfma_f32_32x32x16_bf16 v[32:47], v[230:233], v[140:143], v[32:47]
	s_waitcnt lgkmcnt(0)
	v_mfma_f32_32x32x16_bf16 v[16:31], v[226:229], v[234:237], v[16:31]
	v_mfma_f32_32x32x16_bf16 v[0:15], v[226:229], v[238:241], v[0:15]
	v_mfma_f32_32x32x16_bf16 v[16:31], v[230:233], v[128:131], v[16:31]
	v_mfma_f32_32x32x16_bf16 v[0:15], v[230:233], v[132:135], v[0:15]
	s_add_i32 s84, s84, 0x8000
	s_cmp_eq_u32 s84, 0x18000
	s_cselect_b32 s84, 0, s84
	s_add_i32 s25, s25, 1
	s_cmpk_eq_i32 s25, 0x82
	s_cbranch_scc0 .LattnB_m0
	s_waitcnt vmcnt(0)
	s_barrier

; #define SBAR() __builtin_amdgcn_sched_barrier(0)
; #define PVR(S, DA, DB, vbase) do { S[0] = tr_read<v_rd_off(DA, 0, 0)>(vbase); S[1] = tr_read<v_rd_off(DA, 0, 1)>(vbase); S[2] = tr_read<v_rd_off(DB, 0, 0)>(vbase); S[3] = tr_read<v_rd_off(DB, 0, 1)>(vbase); \
;     S[4] = tr_read<v_rd_off(DA, 1, 0)>(vbase); S[5] = tr_read<v_rd_off(DA, 1, 1)>(vbase); S[6] = tr_read<v_rd_off(DB, 1, 0)>(vbase); S[7] = tr_read<v_rd_off(DB, 1, 1)>(vbase); } while (0)
; #define RAWBAR() do { asm volatile("s_waitcnt lgkmcnt(0)" ::: "memory"); __builtin_amdgcn_s_barrier(); asm volatile("" ::: "memory"); } while (0)
; #define RAWBAR() do { asm volatile("s_waitcnt lgkmcnt(0)" ::: "memory"); __builtin_amdgcn_s_barrier(); asm volatile("" ::: "memory"); } while (0)
; #define RAWBAR() do { asm volatile("s_waitcnt lgkmcnt(0)" ::: "memory"); __builtin_amdgcn_s_barrier(); asm volatile("" ::: "memory"); } while (0)
; #define RAWBAR() do { asm volatile("s_waitcnt lgkmcnt(0)" ::: "memory"); __builtin_amdgcn_s_barrier(); asm volatile("" ::: "memory"); } while (0)
; #define RAWBAR() do { asm volatile("s_waitcnt lgkmcnt(0)" ::: "memory"); __builtin_amdgcn_s_barrier(); asm volatile("" ::: "memory"); } while (0)
; template <int MODE> ...
;     ...
;   for (int j = 0; j < NT; ++j) {
;     const int buf = j & 1;
;     if (j + 1 < NT) { STAGE((j + 1) * KVBLK, buf ^ 1); }
;     const char* Kb = K_lds + buf * 16384;
;     f32x16 pe = {}, po = {};
; #pragma unroll
;     for (int d0 = 0; d0 < 8; d0 += 2) {
;       const bf16x8 k0 = *reinterpret_cast<const bf16x8*>(Kb + KSWZ(krow, (d0 * 16 + hi * 8) * 2));
;       const bf16x8 k1 = *reinterpret_cast<const bf16x8*>(Kb + KSWZ(krow, ((d0 + 1) * 16 + hi * 8) * 2));
;       pe = __builtin_amdgcn_mfma_f32_32x32x16_bf16(k0, qr[d0], pe, 0, 0, 0);
;       po = __builtin_amdgcn_mfma_f32_32x32x16_bf16(k1, qr[d0 + 1], po, 0, 0, 0); }
;     const int vo = vb0 + buf * 32768;
;     s16x4 R0_[8], R1_[8];
;     PVR(R0_, 0, 1, vo);
;     f32x16 p;
; #pragma unroll
;     for (int r = 0; r < 16; ++r) p[r] = __builtin_amdgcn_exp2f(fmaf(pe[r] + po[r], C, negMc));
;     float ps = 0.f;
; #pragma unroll
;     for (int r = 0; r < 16; ++r) ps += p[r];
;     lsum += ps;
;     const bf16x8 own0 = pk8(p, 0), own1 = pk8(p, 8);
;     SBAR();
;     PV_TAIL4(o, vo, vo + 16384, own0, own1);
;     asm volatile("s_waitcnt vmcnt(0)" ::: "memory");
;     RAWBAR();
;   }
.LBB0_1023:
	ds_read_b128 v[230:233], v229 offset:16384
	ds_read_b128 v[234:237], v228 offset:16384
	ds_read_b128 v[238:241], v227 offset:16384
	ds_read_b128 v[242:245], v226 offset:16384
	s_mov_b32 m0, s34
	s_nop 0
	global_load_lds_dwordx4 v225, s[86:87] sc1
	s_add_i32 m0, s34, 0x2000
	s_nop 0
	global_load_lds_dwordx4 v223, s[86:87] sc1
	v_exp_f32_e32 v144, v144
	v_exp_f32_e32 v145, v145
	v_exp_f32_e32 v146, v146
	v_exp_f32_e32 v147, v147
	s_waitcnt lgkmcnt(2)
	v_mfma_f32_32x32x16_bf16 v[128:143], v[230:233], v[188:191], 0
	v_mfma_f32_32x32x16_bf16 v[128:143], v[234:237], v[184:187], v[128:143]
	ds_read_b128 v[230:233], v229 offset:16512
	ds_read_b128 v[234:237], v228 offset:16512
	v_exp_f32_e32 v148, v148
	v_exp_f32_e32 v149, v149
	v_exp_f32_e32 v150, v150
	v_exp_f32_e32 v151, v151
	v_add_f32_e32 v250, v144, v145
	v_add_f32_e32 v250, v146, v250
	v_add_f32_e32 v250, v147, v250
	s_waitcnt lgkmcnt(2)
	v_mfma_f32_32x32x16_bf16 v[128:143], v[238:241], v[180:183], v[128:143]
	v_mfma_f32_32x32x16_bf16 v[128:143], v[242:245], v[176:179], v[128:143]
	ds_read_b128 v[238:241], v227 offset:16512
	ds_read_b128 v[242:245], v226 offset:16512
	v_exp_f32_e32 v152, v152
	v_exp_f32_e32 v153, v153
	v_exp_f32_e32 v154, v154
	v_exp_f32_e32 v155, v155
	v_add_f32_e32 v250, v148, v250
	v_add_f32_e32 v250, v149, v250
	v_add_f32_e32 v250, v150, v250
	v_add_f32_e32 v250, v151, v250
	s_waitcnt lgkmcnt(2)
	v_mfma_f32_32x32x16_bf16 v[128:143], v[230:233], v[172:175], v[128:143]
	v_mfma_f32_32x32x16_bf16 v[128:143], v[234:237], v[168:171], v[128:143]
	v_exp_f32_e32 v156, v156
	v_exp_f32_e32 v157, v157
	v_exp_f32_e32 v158, v158
	v_exp_f32_e32 v159, v159
	v_add_f32_e32 v250, v152, v250
	v_add_f32_e32 v250, v153, v250
	v_add_f32_e32 v250, v154, v250
	v_add_f32_e32 v250, v155, v250
	v_cvt_pk_bf16_f32 v230, v144, v145
	v_cvt_pk_bf16_f32 v231, v146, v147
	v_cvt_pk_bf16_f32 v232, v148, v149
	v_cvt_pk_bf16_f32 v233, v150, v151
	s_waitcnt lgkmcnt(0)
	v_mfma_f32_32x32x16_bf16 v[128:143], v[238:241], v[164:167], v[128:143]
	v_mfma_f32_32x32x16_bf16 v[128:143], v[242:245], v[160:163], v[128:143]
	v_add_u32_e32 v249, s84, v218
	s_add_i32 s85, s84, 0x8000
	s_cmp_eq_u32 s85, 0x18000
	s_cselect_b32 s85, 0, s85
	ds_read_b64_tr_b16 v[238:239], v249 offset:0
	ds_read_b64_tr_b16 v[240:241], v249 offset:2048
	ds_read_b64_tr_b16 v[242:243], v249 offset:512
	ds_read_b64_tr_b16 v[244:245], v249 offset:2560
	ds_read_b64_tr_b16 v[144:145], v249 offset:4096
	ds_read_b64_tr_b16 v[146:147], v249 offset:6144
	ds_read_b64_tr_b16 v[148:149], v249 offset:4608
	ds_read_b64_tr_b16 v[150:151], v249 offset:6656
	v_add_f32_e32 v250, v156, v250
	v_add_f32_e32 v250, v157, v250
	v_add_f32_e32 v250, v158, v250
	v_add_f32_e32 v250, v159, v250
	v_cvt_pk_bf16_f32 v234, v152, v153
	v_cvt_pk_bf16_f32 v235, v154, v155
	v_cvt_pk_bf16_f32 v236, v156, v157
	v_cvt_pk_bf16_f32 v237, v158, v159
	v_add_f32_e32 v219, v219, v250
	ds_read_b64_tr_b16 v[152:153], v249 offset:1024
	ds_read_b64_tr_b16 v[154:155], v249 offset:3072
	ds_read_b64_tr_b16 v[156:157], v249 offset:1536
	ds_read_b64_tr_b16 v[158:159], v249 offset:3584
	s_waitcnt lgkmcnt(8)
	v_mfma_f32_32x32x16_bf16 v[112:127], v[230:233], v[238:241], v[112:127]
	v_mfma_f32_32x32x16_bf16 v[96:111], v[230:233], v[242:245], v[96:111]
	ds_read_b64_tr_b16 v[238:239], v249 offset:5120
	ds_read_b64_tr_b16 v[240:241], v249 offset:7168
	ds_read_b64_tr_b16 v[242:243], v249 offset:5632
	ds_read_b64_tr_b16 v[244:245], v249 offset:7680
	s_add_i32 s30, s85, s34
	s_add_i32 m0, s30, 0x8000
	s_nop 0
	global_load_lds_dwordx4 v222, s[2:3] sc1
	s_waitcnt lgkmcnt(8)
	v_mfma_f32_32x32x16_bf16 v[112:127], v[234:237], v[144:147], v[112:127]
	v_mfma_f32_32x32x16_bf16 v[96:111], v[234:237], v[148:151], v[96:111]
	ds_read_b64_tr_b16 v[144:145], v249 offset:16384
	ds_read_b64_tr_b16 v[146:147], v249 offset:18432
	ds_read_b64_tr_b16 v[148:149], v249 offset:16896
	ds_read_b64_tr_b16 v[150:151], v249 offset:18944
	s_add_i32 s30, s85, s34
	s_add_i32 m0, s30, 0xa000
	s_nop 0
	global_load_lds_dwordx4 v221, s[2:3] sc1
	s_waitcnt lgkmcnt(8)
	v_mfma_f32_32x32x16_bf16 v[80:95], v[230:233], v[152:155], v[80:95]
	v_mfma_f32_32x32x16_bf16 v[64:79], v[230:233], v[156:159], v[64:79]
	ds_read_b64_tr_b16 v[152:153], v249 offset:20480
	ds_read_b64_tr_b16 v[154:155], v249 offset:22528
	ds_read_b64_tr_b16 v[156:157], v249 offset:20992
	ds_read_b64_tr_b16 v[158:159], v249 offset:23040
	s_add_i32 s30, s85, s34
	s_add_i32 m0, s30, 0xc000
	s_nop 0
	global_load_lds_dwordx4 v246, s[2:3] sc1
	s_waitcnt lgkmcnt(8)
	v_mfma_f32_32x32x16_bf16 v[80:95], v[234:237], v[238:241], v[80:95]
	v_mfma_f32_32x32x16_bf16 v[64:79], v[234:237], v[242:245], v[64:79]
	ds_read_b64_tr_b16 v[238:239], v249 offset:17408
	ds_read_b64_tr_b16 v[240:241], v249 offset:19456
	ds_read_b64_tr_b16 v[242:243], v249 offset:17920
	ds_read_b64_tr_b16 v[244:245], v249 offset:19968
	s_add_i32 s30, s85, s34
	s_add_i32 m0, s30, 0xe000
	s_nop 0
	global_load_lds_dwordx4 v247, s[2:3] sc1
	s_waitcnt lgkmcnt(8)
	v_mfma_f32_32x32x16_bf16 v[32:47], v[230:233], v[144:147], v[32:47]
	v_mfma_f32_32x32x16_bf16 v[16:31], v[230:233], v[148:151], v[16:31]
	ds_read_b64_tr_b16 v[144:145], v249 offset:21504
	ds_read_b64_tr_b16 v[146:147], v249 offset:23552
	ds_read_b64_tr_b16 v[148:149], v249 offset:22016
	ds_read_b64_tr_b16 v[150:151], v249 offset:24064
	s_waitcnt lgkmcnt(8)
	v_mfma_f32_32x32x16_bf16 v[32:47], v[234:237], v[152:155], v[32:47]
	v_mfma_f32_32x32x16_bf16 v[16:31], v[234:237], v[156:159], v[16:31]
	s_waitcnt lgkmcnt(0)
	v_mfma_f32_32x32x16_bf16 v[48:63], v[230:233], v[238:241], v[48:63]
	s_waitcnt vmcnt(0)
	s_barrier
; #define SBAR() __builtin_amdgcn_sched_barrier(0)
; #define PVR(S, DA, DB, vbase) do { S[0] = tr_read<v_rd_off(DA, 0, 0)>(vbase); S[1] = tr_read<v_rd_off(DA, 0, 1)>(vbase); S[2] = tr_read<v_rd_off(DB, 0, 0)>(vbase); S[3] = tr_read<v_rd_off(DB, 0, 1)>(vbase); \
;     S[4] = tr_read<v_rd_off(DA, 1, 0)>(vbase); S[5] = tr_read<v_rd_off(DA, 1, 1)>(vbase); S[6] = tr_read<v_rd_off(DB, 1, 0)>(vbase); S[7] = tr_read<v_rd_off(DB, 1, 1)>(vbase); } while (0)
; #define RAWBAR() do { asm volatile("s_waitcnt lgkmcnt(0)" ::: "memory"); __builtin_amdgcn_s_barrier(); asm volatile("" ::: "memory"); } while (0)
; #define RAWBAR() do { asm volatile("s_waitcnt lgkmcnt(0)" ::: "memory"); __builtin_amdgcn_s_barrier(); asm volatile("" ::: "memory"); } while (0)
; #define RAWBAR() do { asm volatile("s_waitcnt lgkmcnt(0)" ::: "memory"); __builtin_amdgcn_s_barrier(); asm volatile("" ::: "memory"); } while (0)
; #define RAWBAR() do { asm volatile("s_waitcnt lgkmcnt(0)" ::: "memory"); __builtin_amdgcn_s_barrier(); asm volatile("" ::: "memory"); } while (0)
; #define RAWBAR() do { asm volatile("s_waitcnt lgkmcnt(0)" ::: "memory"); __builtin_amdgcn_s_barrier(); asm volatile("" ::: "memory"); } while (0)
; template <int MODE> ...
;     ...
;   for (int j = 0; j < NT; ++j) {
;     const int buf = j & 1;
;     if (j + 1 < NT) { STAGE((j + 1) * KVBLK, buf ^ 1); }
;     const char* Kb = K_lds + buf * 16384;
;     f32x16 pe = {}, po = {};
; #pragma unroll
;     for (int d0 = 0; d0 < 8; d0 += 2) {
;       const bf16x8 k0 = *reinterpret_cast<const bf16x8*>(Kb + KSWZ(krow, (d0 * 16 + hi * 8) * 2));
;       const bf16x8 k1 = *reinterpret_cast<const bf16x8*>(Kb + KSWZ(krow, ((d0 + 1) * 16 + hi * 8) * 2));
;       pe = __builtin_amdgcn_mfma_f32_32x32x16_bf16(k0, qr[d0], pe, 0, 0, 0);
;       po = __builtin_amdgcn_mfma_f32_32x32x16_bf16(k1, qr[d0 + 1], po, 0, 0, 0); }
;     const int vo = vb0 + buf * 32768;
;     s16x4 R0_[8], R1_[8];
;     PVR(R0_, 0, 1, vo);
;     f32x16 p;
; #pragma unroll
;     for (int r = 0; r < 16; ++r) p[r] = __builtin_amdgcn_exp2f(fmaf(pe[r] + po[r], C, negMc));
;     float ps = 0.f;
; #pragma unroll
;     for (int r = 0; r < 16; ++r) ps += p[r];
;     lsum += ps;
;     const bf16x8 own0 = pk8(p, 0), own1 = pk8(p, 8);
;     SBAR();
;     PV_TAIL4(o, vo, vo + 16384, own0, own1);
;     asm volatile("s_waitcnt vmcnt(0)" ::: "memory");
;     RAWBAR();
;   }
	s_add_u32 s86, s86, 0x4000
	s_addc_u32 s87, s87, 0
	s_add_u32 s2, s2, 0x8000
	s_addc_u32 s3, s3, 0
	v_mfma_f32_32x32x16_bf16 v[0:15], v[230:233], v[242:245], v[0:15]
	v_mfma_f32_32x32x16_bf16 v[48:63], v[234:237], v[144:147], v[48:63]
	v_mfma_f32_32x32x16_bf16 v[0:15], v[234:237], v[148:151], v[0:15]
	s_add_i32 s84, s84, 0x8000
	s_cmp_eq_u32 s84, 0x18000
	s_cselect_b32 s84, 0, s84
	ds_read_b128 v[230:233], v229 offset:0
	ds_read_b128 v[234:237], v228 offset:0
	ds_read_b128 v[238:241], v227 offset:0
	ds_read_b128 v[242:245], v226 offset:0
	s_add_i32 m0, s34, 0x4000
	s_nop 0
	global_load_lds_dwordx4 v225, s[86:87] sc1
	s_add_i32 m0, s34, 0x6000
	s_nop 0
	global_load_lds_dwordx4 v223, s[86:87] sc1
	v_exp_f32_e32 v128, v128
	v_exp_f32_e32 v129, v129
	v_exp_f32_e32 v130, v130
	v_exp_f32_e32 v131, v131
	s_waitcnt lgkmcnt(2)
	v_mfma_f32_32x32x16_bf16 v[144:159], v[230:233], v[188:191], 0
	v_mfma_f32_32x32x16_bf16 v[144:159], v[234:237], v[184:187], v[144:159]
	ds_read_b128 v[230:233], v229 offset:128
	ds_read_b128 v[234:237], v228 offset:128
	v_exp_f32_e32 v132, v132
	v_exp_f32_e32 v133, v133
	v_exp_f32_e32 v134, v134
	v_exp_f32_e32 v135, v135
	v_add_f32_e32 v250, v128, v129
	v_add_f32_e32 v250, v130, v250
	v_add_f32_e32 v250, v131, v250
	s_waitcnt lgkmcnt(2)
	v_mfma_f32_32x32x16_bf16 v[144:159], v[238:241], v[180:183], v[144:159]
	v_mfma_f32_32x32x16_bf16 v[144:159], v[242:245], v[176:179], v[144:159]
	ds_read_b128 v[238:241], v227 offset:128
	ds_read_b128 v[242:245], v226 offset:128
	v_exp_f32_e32 v136, v136
	v_exp_f32_e32 v137, v137
	v_exp_f32_e32 v138, v138
	v_exp_f32_e32 v139, v139
	v_add_f32_e32 v250, v132, v250
	v_add_f32_e32 v250, v133, v250
	v_add_f32_e32 v250, v134, v250
	v_add_f32_e32 v250, v135, v250
	s_waitcnt lgkmcnt(2)
	v_mfma_f32_32x32x16_bf16 v[144:159], v[230:233], v[172:175], v[144:159]
	v_mfma_f32_32x32x16_bf16 v[144:159], v[234:237], v[168:171], v[144:159]
	v_exp_f32_e32 v140, v140
	v_exp_f32_e32 v141, v141
	v_exp_f32_e32 v142, v142
	v_exp_f32_e32 v143, v143
	v_add_f32_e32 v250, v136, v250
	v_add_f32_e32 v250, v137, v250
	v_add_f32_e32 v250, v138, v250
	v_add_f32_e32 v250, v139, v250
	v_cvt_pk_bf16_f32 v230, v128, v129
	v_cvt_pk_bf16_f32 v231, v130, v131
	v_cvt_pk_bf16_f32 v232, v132, v133
	v_cvt_pk_bf16_f32 v233, v134, v135
	s_waitcnt lgkmcnt(0)
	v_mfma_f32_32x32x16_bf16 v[144:159], v[238:241], v[164:167], v[144:159]
	v_mfma_f32_32x32x16_bf16 v[144:159], v[242:245], v[160:163], v[144:159]
	v_add_u32_e32 v249, s84, v218
	s_add_i32 s85, s84, 0x8000
	s_cmp_eq_u32 s85, 0x18000
	s_cselect_b32 s85, 0, s85
	ds_read_b64_tr_b16 v[238:239], v249 offset:0
	ds_read_b64_tr_b16 v[240:241], v249 offset:2048
	ds_read_b64_tr_b16 v[242:243], v249 offset:512
	ds_read_b64_tr_b16 v[244:245], v249 offset:2560
	ds_read_b64_tr_b16 v[128:129], v249 offset:4096
	ds_read_b64_tr_b16 v[130:131], v249 offset:6144
	ds_read_b64_tr_b16 v[132:133], v249 offset:4608
	ds_read_b64_tr_b16 v[134:135], v249 offset:6656
	v_add_f32_e32 v250, v140, v250
	v_add_f32_e32 v250, v141, v250
	v_add_f32_e32 v250, v142, v250
	v_add_f32_e32 v250, v143, v250
	v_cvt_pk_bf16_f32 v234, v136, v137
	v_cvt_pk_bf16_f32 v235, v138, v139
	v_cvt_pk_bf16_f32 v236, v140, v141
	v_cvt_pk_bf16_f32 v237, v142, v143
	v_add_f32_e32 v219, v219, v250
	ds_read_b64_tr_b16 v[136:137], v249 offset:1024
	ds_read_b64_tr_b16 v[138:139], v249 offset:3072
	ds_read_b64_tr_b16 v[140:141], v249 offset:1536
	ds_read_b64_tr_b16 v[142:143], v249 offset:3584
	s_waitcnt lgkmcnt(8)
	v_mfma_f32_32x32x16_bf16 v[112:127], v[230:233], v[238:241], v[112:127]
	v_mfma_f32_32x32x16_bf16 v[96:111], v[230:233], v[242:245], v[96:111]
	ds_read_b64_tr_b16 v[238:239], v249 offset:5120
	ds_read_b64_tr_b16 v[240:241], v249 offset:7168
	ds_read_b64_tr_b16 v[242:243], v249 offset:5632
	ds_read_b64_tr_b16 v[244:245], v249 offset:7680
	s_add_i32 s30, s85, s34
	s_add_i32 m0, s30, 0x8000
	s_nop 0
	global_load_lds_dwordx4 v222, s[2:3] sc1
	s_waitcnt lgkmcnt(8)
	v_mfma_f32_32x32x16_bf16 v[112:127], v[234:237], v[128:131], v[112:127]
	v_mfma_f32_32x32x16_bf16 v[96:111], v[234:237], v[132:135], v[96:111]
	ds_read_b64_tr_b16 v[128:129], v249 offset:16384
	ds_read_b64_tr_b16 v[130:131], v249 offset:18432
	ds_read_b64_tr_b16 v[132:133], v249 offset:16896
	ds_read_b64_tr_b16 v[134:135], v249 offset:18944
	s_add_i32 s30, s85, s34
	s_add_i32 m0, s30, 0xa000
	s_nop 0
	global_load_lds_dwordx4 v221, s[2:3] sc1
	s_waitcnt lgkmcnt(8)
	v_mfma_f32_32x32x16_bf16 v[80:95], v[230:233], v[136:139], v[80:95]
	v_mfma_f32_32x32x16_bf16 v[64:79], v[230:233], v[140:143], v[64:79]
	ds_read_b64_tr_b16 v[136:137], v249 offset:20480
	ds_read_b64_tr_b16 v[138:139], v249 offset:22528
	ds_read_b64_tr_b16 v[140:141], v249 offset:20992
	ds_read_b64_tr_b16 v[142:143], v249 offset:23040
	s_add_i32 s30, s85, s34
	s_add_i32 m0, s30, 0xc000
	s_nop 0
	global_load_lds_dwordx4 v246, s[2:3] sc1
	s_waitcnt lgkmcnt(8)
	v_mfma_f32_32x32x16_bf16 v[80:95], v[234:237], v[238:241], v[80:95]
	v_mfma_f32_32x32x16_bf16 v[64:79], v[234:237], v[242:245], v[64:79]
	ds_read_b64_tr_b16 v[238:239], v249 offset:17408
	ds_read_b64_tr_b16 v[240:241], v249 offset:19456
	ds_read_b64_tr_b16 v[242:243], v249 offset:17920
	ds_read_b64_tr_b16 v[244:245], v249 offset:19968
	s_add_i32 s30, s85, s34
	s_add_i32 m0, s30, 0xe000
	s_nop 0
	global_load_lds_dwordx4 v247, s[2:3] sc1
	s_waitcnt lgkmcnt(8)
	v_mfma_f32_32x32x16_bf16 v[32:47], v[230:233], v[128:131], v[32:47]
	v_mfma_f32_32x32x16_bf16 v[16:31], v[230:233], v[132:135], v[16:31]
	ds_read_b64_tr_b16 v[128:129], v249 offset:21504
	ds_read_b64_tr_b16 v[130:131], v249 offset:23552
	ds_read_b64_tr_b16 v[132:133], v249 offset:22016
	ds_read_b64_tr_b16 v[134:135], v249 offset:24064
	s_waitcnt lgkmcnt(8)
	v_mfma_f32_32x32x16_bf16 v[32:47], v[234:237], v[136:139], v[32:47]
	v_mfma_f32_32x32x16_bf16 v[16:31], v[234:237], v[140:143], v[16:31]
	s_waitcnt lgkmcnt(0)
	v_mfma_f32_32x32x16_bf16 v[48:63], v[230:233], v[238:241], v[48:63]
	s_waitcnt vmcnt(0)
	s_barrier
	s_add_u32 s86, s86, 0x4000
	s_addc_u32 s87, s87, 0
	s_add_u32 s2, s2, 0x8000
	s_addc_u32 s3, s3, 0
	v_mfma_f32_32x32x16_bf16 v[0:15], v[230:233], v[242:245], v[0:15]
	v_mfma_f32_32x32x16_bf16 v[48:63], v[234:237], v[128:131], v[48:63]
	v_mfma_f32_32x32x16_bf16 v[0:15], v[234:237], v[132:135], v[0:15]
	s_add_i32 s84, s84, 0x8000
	s_cmp_eq_u32 s84, 0x18000
	s_cselect_b32 s84, 0, s84
	s_add_i32 s40, s40, 1
	s_cmpk_eq_i32 s40, 0x82
	s_cbranch_scc0 .LBB0_1023
	s_barrier
	s_branch .Lattn_join_m1
; #define SBAR() __builtin_amdgcn_sched_barrier(0)
; #define PVR(S, DA, DB, vbase) do { S[0] = tr_read<v_rd_off(DA, 0, 0)>(vbase); S[1] = tr_read<v_rd_off(DA, 0, 1)>(vbase); S[2] = tr_read<v_rd_off(DB, 0, 0)>(vbase); S[3] = tr_read<v_rd_off(DB, 0, 1)>(vbase); \
;     S[4] = tr_read<v_rd_off(DA, 1, 0)>(vbase); S[5] = tr_read<v_rd_off(DA, 1, 1)>(vbase); S[6] = tr_read<v_rd_off(DB, 1, 0)>(vbase); S[7] = tr_read<v_rd_off(DB, 1, 1)>(vbase); } while (0)
; #define RAWBAR() do { asm volatile("s_waitcnt lgkmcnt(0)" ::: "memory"); __builtin_amdgcn_s_barrier(); asm volatile("" ::: "memory"); } while (0)
; #define RAWBAR() do { asm volatile("s_waitcnt lgkmcnt(0)" ::: "memory"); __builtin_amdgcn_s_barrier(); asm volatile("" ::: "memory"); } while (0)
; #define RAWBAR() do { asm volatile("s_waitcnt lgkmcnt(0)" ::: "memory"); __builtin_amdgcn_s_barrier(); asm volatile("" ::: "memory"); } while (0)
; #define RAWBAR() do { asm volatile("s_waitcnt lgkmcnt(0)" ::: "memory"); __builtin_amdgcn_s_barrier(); asm volatile("" ::: "memory"); } while (0)
; #define RAWBAR() do { asm volatile("s_waitcnt lgkmcnt(0)" ::: "memory"); __builtin_amdgcn_s_barrier(); asm volatile("" ::: "memory"); } while (0)
; template <int MODE> ...
;     ...
;   for (int j = 0; j < NT; ++j) {
;     const int buf = j & 1;
;     if (j + 1 < NT) { STAGE((j + 1) * KVBLK, buf ^ 1); }
;     const char* Kb = K_lds + buf * 16384;
;     f32x16 pe = {}, po = {};
; #pragma unroll
;     for (int d0 = 0; d0 < 8; d0 += 2) {
;       const bf16x8 k0 = *reinterpret_cast<const bf16x8*>(Kb + KSWZ(krow, (d0 * 16 + hi * 8) * 2));
;       const bf16x8 k1 = *reinterpret_cast<const bf16x8*>(Kb + KSWZ(krow, ((d0 + 1) * 16 + hi * 8) * 2));
;       pe = __builtin_amdgcn_mfma_f32_32x32x16_bf16(k0, qr[d0], pe, 0, 0, 0);
;       po = __builtin_amdgcn_mfma_f32_32x32x16_bf16(k1, qr[d0 + 1], po, 0, 0, 0); }
;     const int vo = vb0 + buf * 32768;
;     s16x4 R0_[8], R1_[8];
;     PVR(R0_, 0, 1, vo);
;     f32x16 p;
; #pragma unroll
;     for (int r = 0; r < 16; ++r) p[r] = __builtin_amdgcn_exp2f(fmaf(pe[r] + po[r], C, negMc));
;     float ps = 0.f;
; #pragma unroll
;     for (int r = 0; r < 16; ++r) ps += p[r];
;     lsum += ps;
;     const bf16x8 own0 = pk8(p, 0), own1 = pk8(p, 8);
;     SBAR();
;     PV_TAIL4(o, vo, vo + 16384, own0, own1);
;     asm volatile("s_waitcnt vmcnt(0)" ::: "memory");
;     RAWBAR();
;   }
.LattnBpre_m1:
	s_mov_b32 m0, s34
	s_nop 0
	global_load_lds_dwordx4 v225, s[86:87] sc1
	s_add_i32 m0, s34, 0x2000
	s_nop 0
	global_load_lds_dwordx4 v223, s[86:87] sc1
	s_add_i32 s85, s84, 0x8000
	s_cmp_eq_u32 s85, 0x18000
	s_cselect_b32 s85, 0, s85
	s_add_i32 s30, s85, s34
	s_add_i32 m0, s30, 0x8000
	s_nop 0
	global_load_lds_dwordx4 v222, s[2:3] sc1
	s_add_i32 s30, s85, s34
	s_add_i32 m0, s30, 0xa000
	s_nop 0
	global_load_lds_dwordx4 v221, s[2:3] sc1
	s_add_i32 s30, s85, s34
	s_add_i32 m0, s30, 0xc000
	s_nop 0
	global_load_lds_dwordx4 v246, s[2:3] sc1
	s_add_i32 s30, s85, s34
	s_add_i32 m0, s30, 0xe000
	s_nop 0
	global_load_lds_dwordx4 v247, s[2:3] sc1
.LattnB_m1:
	ds_read_b128 v[230:233], v229 offset:16384
	ds_read_b128 v[234:237], v228 offset:16384
	ds_read_b128 v[238:241], v227 offset:16384
	ds_read_b128 v[242:245], v226 offset:16384
	v_exp_f32_e32 v144, v144
	v_exp_f32_e32 v145, v145
	v_exp_f32_e32 v146, v146
	v_exp_f32_e32 v147, v147
	s_waitcnt lgkmcnt(2)
	v_mfma_f32_32x32x16_bf16 v[128:143], v[230:233], v[188:191], 0
	v_mfma_f32_32x32x16_bf16 v[128:143], v[234:237], v[184:187], v[128:143]
	ds_read_b128 v[230:233], v229 offset:16512
	ds_read_b128 v[234:237], v228 offset:16512
	v_exp_f32_e32 v148, v148
	v_exp_f32_e32 v149, v149
	v_exp_f32_e32 v150, v150
	v_exp_f32_e32 v151, v151
	v_add_f32_e32 v250, v144, v145
	v_add_f32_e32 v250, v146, v250
	v_add_f32_e32 v250, v147, v250
	s_waitcnt lgkmcnt(2)
	v_mfma_f32_32x32x16_bf16 v[128:143], v[238:241], v[180:183], v[128:143]
	v_mfma_f32_32x32x16_bf16 v[128:143], v[242:245], v[176:179], v[128:143]
	ds_read_b128 v[238:241], v227 offset:16512
	ds_read_b128 v[242:245], v226 offset:16512
	v_exp_f32_e32 v152, v152
	v_exp_f32_e32 v153, v153
	v_exp_f32_e32 v154, v154
	v_exp_f32_e32 v155, v155
	v_add_f32_e32 v250, v148, v250
	v_add_f32_e32 v250, v149, v250
	v_add_f32_e32 v250, v150, v250
	v_add_f32_e32 v250, v151, v250
	s_waitcnt lgkmcnt(2)
	v_mfma_f32_32x32x16_bf16 v[128:143], v[230:233], v[172:175], v[128:143]
	v_mfma_f32_32x32x16_bf16 v[128:143], v[234:237], v[168:171], v[128:143]
	v_exp_f32_e32 v156, v156
	v_exp_f32_e32 v157, v157
	v_exp_f32_e32 v158, v158
	v_exp_f32_e32 v159, v159
	v_add_f32_e32 v250, v152, v250
	v_add_f32_e32 v250, v153, v250
	v_add_f32_e32 v250, v154, v250
	v_add_f32_e32 v250, v155, v250
	v_cvt_pk_bf16_f32 v230, v144, v145
	v_cvt_pk_bf16_f32 v231, v146, v147
	v_cvt_pk_bf16_f32 v232, v148, v149
	v_cvt_pk_bf16_f32 v233, v150, v151
	s_waitcnt lgkmcnt(0)
	v_mfma_f32_32x32x16_bf16 v[128:143], v[238:241], v[164:167], v[128:143]
	v_mfma_f32_32x32x16_bf16 v[128:143], v[242:245], v[160:163], v[128:143]
	s_waitcnt vmcnt(0)
	s_barrier
	s_add_u32 s86, s86, 0x4000
	s_addc_u32 s87, s87, 0
	s_add_u32 s2, s2, 0x8000
	s_addc_u32 s3, s3, 0
	s_add_i32 m0, s34, 0x4000
	s_nop 0
	global_load_lds_dwordx4 v225, s[86:87] sc1
	s_add_i32 m0, s34, 0x6000
	s_nop 0
	global_load_lds_dwordx4 v223, s[86:87] sc1
	v_add_u32_e32 v249, s84, v218
	s_sub_u32 s85, s84, 0x8000
	s_cmp_eq_u32 s84, 0
	s_cselect_b32 s85, 0x10000, s85
	ds_read_b64_tr_b16 v[238:239], v249 offset:0
	ds_read_b64_tr_b16 v[240:241], v249 offset:2048
	ds_read_b64_tr_b16 v[242:243], v249 offset:512
	ds_read_b64_tr_b16 v[244:245], v249 offset:2560
	ds_read_b64_tr_b16 v[144:145], v249 offset:4096
	ds_read_b64_tr_b16 v[146:147], v249 offset:6144
	ds_read_b64_tr_b16 v[148:149], v249 offset:4608
	ds_read_b64_tr_b16 v[150:151], v249 offset:6656
	v_add_f32_e32 v250, v156, v250
	v_add_f32_e32 v250, v157, v250
	v_add_f32_e32 v250, v158, v250
	v_add_f32_e32 v250, v159, v250
	v_cvt_pk_bf16_f32 v234, v152, v153
	v_cvt_pk_bf16_f32 v235, v154, v155
	v_cvt_pk_bf16_f32 v236, v156, v157
	v_cvt_pk_bf16_f32 v237, v158, v159
	v_add_f32_e32 v219, v219, v250
	ds_read_b64_tr_b16 v[152:153], v249 offset:1024
	ds_read_b64_tr_b16 v[154:155], v249 offset:3072
	ds_read_b64_tr_b16 v[156:157], v249 offset:1536
	ds_read_b64_tr_b16 v[158:159], v249 offset:3584
	s_waitcnt lgkmcnt(8)
	v_mfma_f32_32x32x16_bf16 v[112:127], v[230:233], v[238:241], v[112:127]
	v_mfma_f32_32x32x16_bf16 v[96:111], v[230:233], v[242:245], v[96:111]
	ds_read_b64_tr_b16 v[238:239], v249 offset:5120
	ds_read_b64_tr_b16 v[240:241], v249 offset:7168
	ds_read_b64_tr_b16 v[242:243], v249 offset:5632
	ds_read_b64_tr_b16 v[244:245], v249 offset:7680
	s_add_i32 s30, s85, s34
	s_add_i32 m0, s30, 0x8000
	s_nop 0
	global_load_lds_dwordx4 v222, s[2:3] sc1
	s_waitcnt lgkmcnt(8)
	v_mfma_f32_32x32x16_bf16 v[112:127], v[234:237], v[144:147], v[112:127]
	v_mfma_f32_32x32x16_bf16 v[96:111], v[234:237], v[148:151], v[96:111]
	ds_read_b64_tr_b16 v[144:145], v249 offset:16384
	ds_read_b64_tr_b16 v[146:147], v249 offset:18432
	ds_read_b64_tr_b16 v[148:149], v249 offset:16896
	ds_read_b64_tr_b16 v[150:151], v249 offset:18944
	s_add_i32 s30, s85, s34
	s_add_i32 m0, s30, 0xa000
	s_nop 0
	global_load_lds_dwordx4 v221, s[2:3] sc1
	s_waitcnt lgkmcnt(8)
	v_mfma_f32_32x32x16_bf16 v[80:95], v[230:233], v[152:155], v[80:95]
	v_mfma_f32_32x32x16_bf16 v[64:79], v[230:233], v[156:159], v[64:79]
	ds_read_b64_tr_b16 v[152:153], v249 offset:20480
	ds_read_b64_tr_b16 v[154:155], v249 offset:22528
	ds_read_b64_tr_b16 v[156:157], v249 offset:20992
	ds_read_b64_tr_b16 v[158:159], v249 offset:23040
	s_add_i32 s30, s85, s34
	s_add_i32 m0, s30, 0xc000
	s_nop 0
	global_load_lds_dwordx4 v246, s[2:3] sc1
	s_waitcnt lgkmcnt(8)
	v_mfma_f32_32x32x16_bf16 v[80:95], v[234:237], v[238:241], v[80:95]
	v_mfma_f32_32x32x16_bf16 v[64:79], v[234:237], v[242:245], v[64:79]
	ds_read_b64_tr_b16 v[238:239], v249 offset:17408
	ds_read_b64_tr_b16 v[240:241], v249 offset:19456
	ds_read_b64_tr_b16 v[242:243], v249 offset:17920
	ds_read_b64_tr_b16 v[244:245], v249 offset:19968
	s_add_i32 s30, s85, s34
	s_add_i32 m0, s30, 0xe000
	s_nop 0
	global_load_lds_dwordx4 v247, s[2:3] sc1
	s_waitcnt lgkmcnt(8)
; #define SBAR() __builtin_amdgcn_sched_barrier(0)
; #define PVR(S, DA, DB, vbase) do { S[0] = tr_read<v_rd_off(DA, 0, 0)>(vbase); S[1] = tr_read<v_rd_off(DA, 0, 1)>(vbase); S[2] = tr_read<v_rd_off(DB, 0, 0)>(vbase); S[3] = tr_read<v_rd_off(DB, 0, 1)>(vbase); \
;     S[4] = tr_read<v_rd_off(DA, 1, 0)>(vbase); S[5] = tr_read<v_rd_off(DA, 1, 1)>(vbase); S[6] = tr_read<v_rd_off(DB, 1, 0)>(vbase); S[7] = tr_read<v_rd_off(DB, 1, 1)>(vbase); } while (0)
; #define RAWBAR() do { asm volatile("s_waitcnt lgkmcnt(0)" ::: "memory"); __builtin_amdgcn_s_barrier(); asm volatile("" ::: "memory"); } while (0)
; #define RAWBAR() do { asm volatile("s_waitcnt lgkmcnt(0)" ::: "memory"); __builtin_amdgcn_s_barrier(); asm volatile("" ::: "memory"); } while (0)
; #define RAWBAR() do { asm volatile("s_waitcnt lgkmcnt(0)" ::: "memory"); __builtin_amdgcn_s_barrier(); asm volatile("" ::: "memory"); } while (0)
; #define RAWBAR() do { asm volatile("s_waitcnt lgkmcnt(0)" ::: "memory"); __builtin_amdgcn_s_barrier(); asm volatile("" ::: "memory"); } while (0)
; #define RAWBAR() do { asm volatile("s_waitcnt lgkmcnt(0)" ::: "memory"); __builtin_amdgcn_s_barrier(); asm volatile("" ::: "memory"); } while (0)
; template <int MODE> ...
;     ...
;   for (int j = 0; j < NT; ++j) {
;     const int buf = j & 1;
;     if (j + 1 < NT) { STAGE((j + 1) * KVBLK, buf ^ 1); }
;     const char* Kb = K_lds + buf * 16384;
;     f32x16 pe = {}, po = {};
; #pragma unroll
;     for (int d0 = 0; d0 < 8; d0 += 2) {
;       const bf16x8 k0 = *reinterpret_cast<const bf16x8*>(Kb + KSWZ(krow, (d0 * 16 + hi * 8) * 2));
;       const bf16x8 k1 = *reinterpret_cast<const bf16x8*>(Kb + KSWZ(krow, ((d0 + 1) * 16 + hi * 8) * 2));
;       pe = __builtin_amdgcn_mfma_f32_32x32x16_bf16(k0, qr[d0], pe, 0, 0, 0);
;       po = __builtin_amdgcn_mfma_f32_32x32x16_bf16(k1, qr[d0 + 1], po, 0, 0, 0); }
;     const int vo = vb0 + buf * 32768;
;     s16x4 R0_[8], R1_[8];
;     PVR(R0_, 0, 1, vo);
;     f32x16 p;
; #pragma unroll
;     for (int r = 0; r < 16; ++r) p[r] = __builtin_amdgcn_exp2f(fmaf(pe[r] + po[r], C, negMc));
;     float ps = 0.f;
; #pragma unroll
;     for (int r = 0; r < 16; ++r) ps += p[r];
;     lsum += ps;
;     const bf16x8 own0 = pk8(p, 0), own1 = pk8(p, 8);
;     SBAR();
;     PV_TAIL4(o, vo, vo + 16384, own0, own1);
;     asm volatile("s_waitcnt vmcnt(0)" ::: "memory");
;     RAWBAR();
;   }
	v_mfma_f32_32x32x16_bf16 v[32:47], v[230:233], v[144:147], v[32:47]
	v_mfma_f32_32x32x16_bf16 v[16:31], v[230:233], v[148:151], v[16:31]
	ds_read_b64_tr_b16 v[144:145], v249 offset:21504
	ds_read_b64_tr_b16 v[146:147], v249 offset:23552
	ds_read_b64_tr_b16 v[148:149], v249 offset:22016
	ds_read_b64_tr_b16 v[150:151], v249 offset:24064
	s_waitcnt lgkmcnt(8)
	v_mfma_f32_32x32x16_bf16 v[32:47], v[234:237], v[152:155], v[32:47]
	v_mfma_f32_32x32x16_bf16 v[16:31], v[234:237], v[156:159], v[16:31]
	s_waitcnt lgkmcnt(0)
	v_mfma_f32_32x32x16_bf16 v[48:63], v[230:233], v[238:241], v[48:63]
	v_mfma_f32_32x32x16_bf16 v[0:15], v[230:233], v[242:245], v[0:15]
	v_mfma_f32_32x32x16_bf16 v[48:63], v[234:237], v[144:147], v[48:63]
	v_mfma_f32_32x32x16_bf16 v[0:15], v[234:237], v[148:151], v[0:15]
	s_add_i32 s84, s84, 0x8000
	s_cmp_eq_u32 s84, 0x18000
	s_cselect_b32 s84, 0, s84
	ds_read_b128 v[230:233], v229 offset:0
	ds_read_b128 v[234:237], v228 offset:0
	ds_read_b128 v[238:241], v227 offset:0
	ds_read_b128 v[242:245], v226 offset:0
	v_exp_f32_e32 v128, v128
	v_exp_f32_e32 v129, v129
	v_exp_f32_e32 v130, v130
	v_exp_f32_e32 v131, v131
	s_waitcnt lgkmcnt(2)
	v_mfma_f32_32x32x16_bf16 v[144:159], v[230:233], v[188:191], 0
	v_mfma_f32_32x32x16_bf16 v[144:159], v[234:237], v[184:187], v[144:159]
	ds_read_b128 v[230:233], v229 offset:128
	ds_read_b128 v[234:237], v228 offset:128
	v_exp_f32_e32 v132, v132
	v_exp_f32_e32 v133, v133
	v_exp_f32_e32 v134, v134
	v_exp_f32_e32 v135, v135
	v_add_f32_e32 v250, v128, v129
	v_add_f32_e32 v250, v130, v250
	v_add_f32_e32 v250, v131, v250
	s_waitcnt lgkmcnt(2)
	v_mfma_f32_32x32x16_bf16 v[144:159], v[238:241], v[180:183], v[144:159]
	v_mfma_f32_32x32x16_bf16 v[144:159], v[242:245], v[176:179], v[144:159]
	ds_read_b128 v[238:241], v227 offset:128
	ds_read_b128 v[242:245], v226 offset:128
	v_exp_f32_e32 v136, v136
	v_exp_f32_e32 v137, v137
	v_exp_f32_e32 v138, v138
	v_exp_f32_e32 v139, v139
	v_add_f32_e32 v250, v132, v250
	v_add_f32_e32 v250, v133, v250
	v_add_f32_e32 v250, v134, v250
	v_add_f32_e32 v250, v135, v250
	s_waitcnt lgkmcnt(2)
	v_mfma_f32_32x32x16_bf16 v[144:159], v[230:233], v[172:175], v[144:159]
	v_mfma_f32_32x32x16_bf16 v[144:159], v[234:237], v[168:171], v[144:159]
	v_exp_f32_e32 v140, v140
	v_exp_f32_e32 v141, v141
	v_exp_f32_e32 v142, v142
	v_exp_f32_e32 v143, v143
	v_add_f32_e32 v250, v136, v250
	v_add_f32_e32 v250, v137, v250
	v_add_f32_e32 v250, v138, v250
	v_add_f32_e32 v250, v139, v250
	v_cvt_pk_bf16_f32 v230, v128, v129
	v_cvt_pk_bf16_f32 v231, v130, v131
	v_cvt_pk_bf16_f32 v232, v132, v133
	v_cvt_pk_bf16_f32 v233, v134, v135
	s_waitcnt lgkmcnt(0)
	v_mfma_f32_32x32x16_bf16 v[144:159], v[238:241], v[164:167], v[144:159]
	v_mfma_f32_32x32x16_bf16 v[144:159], v[242:245], v[160:163], v[144:159]
	s_waitcnt vmcnt(0)
	s_barrier
	s_add_u32 s86, s86, 0x4000
	s_addc_u32 s87, s87, 0
	s_add_u32 s2, s2, 0x8000
	s_addc_u32 s3, s3, 0
	s_mov_b32 m0, s34
	s_nop 0
	global_load_lds_dwordx4 v225, s[86:87] sc1
	s_add_i32 m0, s34, 0x2000
	s_nop 0
	global_load_lds_dwordx4 v223, s[86:87] sc1
	v_add_u32_e32 v249, s84, v218
	s_sub_u32 s85, s84, 0x8000
	s_cmp_eq_u32 s84, 0
	s_cselect_b32 s85, 0x10000, s85
	ds_read_b64_tr_b16 v[238:239], v249 offset:0
	ds_read_b64_tr_b16 v[240:241], v249 offset:2048
	ds_read_b64_tr_b16 v[242:243], v249 offset:512
	ds_read_b64_tr_b16 v[244:245], v249 offset:2560
	ds_read_b64_tr_b16 v[128:129], v249 offset:4096
	ds_read_b64_tr_b16 v[130:131], v249 offset:6144
	ds_read_b64_tr_b16 v[132:133], v249 offset:4608
	ds_read_b64_tr_b16 v[134:135], v249 offset:6656
	v_add_f32_e32 v250, v140, v250
	v_add_f32_e32 v250, v141, v250
	v_add_f32_e32 v250, v142, v250
	v_add_f32_e32 v250, v143, v250
	v_cvt_pk_bf16_f32 v234, v136, v137
	v_cvt_pk_bf16_f32 v235, v138, v139
	v_cvt_pk_bf16_f32 v236, v140, v141
	v_cvt_pk_bf16_f32 v237, v142, v143
	v_add_f32_e32 v219, v219, v250
	ds_read_b64_tr_b16 v[136:137], v249 offset:1024
	ds_read_b64_tr_b16 v[138:139], v249 offset:3072
	ds_read_b64_tr_b16 v[140:141], v249 offset:1536
	ds_read_b64_tr_b16 v[142:143], v249 offset:3584
	s_waitcnt lgkmcnt(8)
	v_mfma_f32_32x32x16_bf16 v[112:127], v[230:233], v[238:241], v[112:127]
	v_mfma_f32_32x32x16_bf16 v[96:111], v[230:233], v[242:245], v[96:111]
	ds_read_b64_tr_b16 v[238:239], v249 offset:5120
	ds_read_b64_tr_b16 v[240:241], v249 offset:7168
	ds_read_b64_tr_b16 v[242:243], v249 offset:5632
	ds_read_b64_tr_b16 v[244:245], v249 offset:7680
	s_add_i32 s30, s85, s34
	s_add_i32 m0, s30, 0x8000
	s_nop 0
	global_load_lds_dwordx4 v222, s[2:3] sc1
	s_waitcnt lgkmcnt(8)
	v_mfma_f32_32x32x16_bf16 v[112:127], v[234:237], v[128:131], v[112:127]
	v_mfma_f32_32x32x16_bf16 v[96:111], v[234:237], v[132:135], v[96:111]
	ds_read_b64_tr_b16 v[128:129], v249 offset:16384
	ds_read_b64_tr_b16 v[130:131], v249 offset:18432
	ds_read_b64_tr_b16 v[132:133], v249 offset:16896
	ds_read_b64_tr_b16 v[134:135], v249 offset:18944
	s_add_i32 s30, s85, s34
	s_add_i32 m0, s30, 0xa000
	s_nop 0
	global_load_lds_dwordx4 v221, s[2:3] sc1
	s_waitcnt lgkmcnt(8)
	v_mfma_f32_32x32x16_bf16 v[80:95], v[230:233], v[136:139], v[80:95]
	v_mfma_f32_32x32x16_bf16 v[64:79], v[230:233], v[140:143], v[64:79]
	ds_read_b64_tr_b16 v[136:137], v249 offset:20480
	ds_read_b64_tr_b16 v[138:139], v249 offset:22528
	ds_read_b64_tr_b16 v[140:141], v249 offset:20992
	ds_read_b64_tr_b16 v[142:143], v249 offset:23040
	s_add_i32 s30, s85, s34
	s_add_i32 m0, s30, 0xc000
	s_nop 0
	global_load_lds_dwordx4 v246, s[2:3] sc1
	s_waitcnt lgkmcnt(8)
	v_mfma_f32_32x32x16_bf16 v[80:95], v[234:237], v[238:241], v[80:95]
	v_mfma_f32_32x32x16_bf16 v[64:79], v[234:237], v[242:245], v[64:79]
	ds_read_b64_tr_b16 v[238:239], v249 offset:17408
	ds_read_b64_tr_b16 v[240:241], v249 offset:19456
	ds_read_b64_tr_b16 v[242:243], v249 offset:17920
	ds_read_b64_tr_b16 v[244:245], v249 offset:19968
	s_add_i32 s30, s85, s34
	s_add_i32 m0, s30, 0xe000
	s_nop 0
	global_load_lds_dwordx4 v247, s[2:3] sc1
	s_waitcnt lgkmcnt(8)
	v_mfma_f32_32x32x16_bf16 v[32:47], v[230:233], v[128:131], v[32:47]
	v_mfma_f32_32x32x16_bf16 v[16:31], v[230:233], v[132:135], v[16:31]
	ds_read_b64_tr_b16 v[128:129], v249 offset:21504
	ds_read_b64_tr_b16 v[130:131], v249 offset:23552
	ds_read_b64_tr_b16 v[132:133], v249 offset:22016
	ds_read_b64_tr_b16 v[134:135], v249 offset:24064
	s_waitcnt lgkmcnt(8)
	v_mfma_f32_32x32x16_bf16 v[32:47], v[234:237], v[136:139], v[32:47]
	v_mfma_f32_32x32x16_bf16 v[16:31], v[234:237], v[140:143], v[16:31]
	s_waitcnt lgkmcnt(0)
	v_mfma_f32_32x32x16_bf16 v[48:63], v[230:233], v[238:241], v[48:63]
	v_mfma_f32_32x32x16_bf16 v[0:15], v[230:233], v[242:245], v[0:15]
	v_mfma_f32_32x32x16_bf16 v[48:63], v[234:237], v[128:131], v[48:63]
	v_mfma_f32_32x32x16_bf16 v[0:15], v[234:237], v[132:135], v[0:15]
	s_add_i32 s84, s84, 0x8000
	s_cmp_eq_u32 s84, 0x18000
	s_cselect_b32 s84, 0, s84
	s_add_i32 s40, s40, 1
	s_cmpk_eq_i32 s40, 0x82
	s_cbranch_scc0 .LattnB_m1
	s_waitcnt vmcnt(0)
	s_barrier
